# STATIC-PRIO on the best: per-segment s_setprio toggling removed from the 4 GEMM loops, one static priority raise for the trailing wave half (waves 4-7) at phase entry
# speedup vs baseline: 1.0027x; 1.0027x over previous
.LBB0_129:
	s_andn2_b64 vcc, exec, s[0:1]
	v_readlane_b32 s17, v251, 20
	s_cbranch_vccnz .LBB0_198
	v_readlane_b32 s2, v251, 52
	v_readlane_b32 s3, v251, 53
	v_readlane_b32 s0, v251, 21
	s_andn2_b64 vcc, exec, s[2:3]
	s_waitcnt vmcnt(0)
	v_mbcnt_lo_u32_b32 v3, -1, 0
	v_mbcnt_hi_u32_b32 v3, -1, v3
	s_cbranch_vccnz .LBB0_146
	s_lshl_b32 s26, s0, 10
	v_lshl_add_u32 v0, v3, 4, s26
	s_waitcnt vmcnt(22)
	v_add_u32_e32 v4, 0x2000, v0
	v_ashrrev_i32_e32 v2, 31, v4
	v_lshrrev_b32_e32 v2, 22, v2
	v_add_u32_e32 v2, v4, v2
	v_ashrrev_i32_e32 v2, 10, v2
	v_mul_i32_i24_e32 v5, 0x400, v2
	v_sub_u32_e32 v4, v4, v5
	v_lshrrev_b32_e32 v5, 4, v4
	v_bitop3_b32 v5, v5, v4, 32 bitop3:0x6c
	v_ashrrev_i32_e32 v4, 31, v5
	v_lshrrev_b32_e32 v4, 26, v4
	v_add_u32_e32 v6, v5, v4
	v_ashrrev_i32_e32 v4, 6, v6
	v_lshlrev_b32_e32 v7, 3, v2
	v_and_b32_e32 v6, 0xffc0, v6
	v_and_b32_e32 v7, -16, v7
	v_sub_u32_e32 v5, v5, v6
	v_add_u32_e32 v7, v4, v7
	v_lshrrev_b16_e32 v6, 7, v5
	s_waitcnt vmcnt(21)
	v_and_b32_e32 v8, 3, v4
	s_mov_b32 s2, 0x7ffe0
	v_lshrrev_b32_e32 v9, 2, v7
	v_lshlrev_b32_e32 v10, 1, v7
	v_and_b32_e32 v6, 1, v6
	v_and_or_b32 v8, v7, s2, v8
	v_and_b32_e32 v9, 4, v9
	v_and_b32_e32 v10, 24, v10
	v_add_u16_e32 v5, v5, v6
	v_or3_b32 v8, v8, v9, v10
	v_lshlrev_b32_e32 v9, 5, v2
	v_ashrrev_i16_sdwa v5, v212, sext(v5) dst_sel:DWORD dst_unused:UNUSED_PAD src0_sel:DWORD src1_sel:BYTE_0
	v_and_b32_e32 v9, 32, v9
	v_bfe_i32 v5, v5, 0, 16
	v_add_lshl_u32 v6, v9, v5, 1
	v_lshl_add_u32 v130, v8, 13, v6
	v_lshl_add_u32 v132, v7, 13, v6
	v_ashrrev_i32_e32 v6, 31, v0
	v_lshrrev_b32_e32 v6, 22, v6
	v_add_u32_e32 v6, v0, v6
	v_ashrrev_i32_e32 v6, 10, v6
	v_mul_i32_i24_e32 v7, 0x400, v6
	v_sub_u32_e32 v0, v0, v7
	v_lshrrev_b32_e32 v7, 4, v0
	v_bitop3_b32 v0, v7, v0, 32 bitop3:0x6c
	v_ashrrev_i32_e32 v7, 31, v0
	v_lshrrev_b32_e32 v7, 26, v7
	v_add_u32_e32 v8, v0, v7
	v_lshlrev_b32_e32 v9, 3, v6
	v_ashrrev_i32_e32 v7, 6, v8
	v_and_b32_e32 v9, -16, v9
	v_add_u32_e32 v9, v7, v9
	v_and_b32_e32 v10, 3, v7
	v_lshrrev_b32_e32 v11, 2, v9
	s_waitcnt vmcnt(20)
	v_lshlrev_b32_e32 v12, 1, v9
	v_and_b32_e32 v8, 0xc0, v8
	v_and_or_b32 v10, v9, s2, v10
	v_and_b32_e32 v11, 4, v11
	v_and_b32_e32 v12, 24, v12
	v_sub_u32_e32 v0, v0, v8
	s_ashr_i32 s1, s0, 2
	v_or3_b32 v10, v10, v11, v12
	v_lshlrev_b32_e32 v11, 5, v6
	v_ashrrev_i16_sdwa v0, v212, sext(v0) dst_sel:DWORD dst_unused:UNUSED_PAD src0_sel:DWORD src1_sel:BYTE_0
	v_readlane_b32 s2, v253, 39
	v_readlane_b32 s4, v255, 31
	v_and_b32_e32 v11, 32, v11
	v_bfe_i32 v8, v0, 0, 16
	v_readlane_b32 s3, v253, 40
	s_add_u32 s22, s4, s2
	v_readlane_b32 s2, v255, 32
	v_add_lshl_u32 v11, v11, v8, 1
	s_addc_u32 s23, s2, s3
	s_add_i32 s31, s26, 0
	v_lshl_add_u32 v0, v10, 13, v11
	s_add_i32 m0, s31, 0x10000
	v_lshl_add_u32 v134, v9, 13, v11
	global_load_lds_dwordx4 v0, s[22:23]
	s_add_i32 m0, s31, 0x12000
	s_add_u32 s2, s22, 0x100000
	global_load_lds_dwordx4 v130, s[22:23]
	s_addc_u32 s3, s23, 0
	s_add_i32 m0, s31, 0x14000
	s_add_i32 s36, s31, 0x2000
	global_load_lds_dwordx4 v0, s[2:3]
	s_add_i32 m0, s31, 0x16000
	s_add_i32 s37, s31, 0x4000
	global_load_lds_dwordx4 v130, s[2:3]
	v_readlane_b32 s2, v253, 43
	s_mov_b32 m0, s31
	v_readlane_b32 s3, v253, 44
	s_add_i32 s38, s31, 0x6000
	s_cmp_eq_u32 s1, 1
	s_mov_b32 s54, s40
	s_nop 1
	global_load_lds_dwordx4 v134, s[2:3]
	s_mov_b32 m0, s36
	s_nop 0
	global_load_lds_dwordx4 v132, s[2:3]
	v_readlane_b32 s2, v253, 45
	s_mov_b32 m0, s37
	v_readlane_b32 s3, v253, 46
	s_nop 4
	global_load_lds_dwordx4 v134, s[2:3]
	s_mov_b32 m0, s38
	s_nop 0
	global_load_lds_dwordx4 v132, s[2:3]
	s_cselect_b64 s[2:3], -1, 0
	s_cmp_lg_u32 s1, 1
	s_cbranch_scc1 .LBB0_133
	s_barrier
	s_setprio 1

.LBB0_139:
	s_add_i32 s49, 0, 0x10000
	s_add_i32 s52, 0, 0x14000
	v_add_u32_e32 v156, s49, v145
	v_add_u32_e32 v172, s52, v145
	ds_read_b128 v[140:143], v156
	ds_read_b128 v[148:151], v156 offset:1024
	ds_read_b128 v[152:155], v156 offset:2048
	ds_read_b128 v[156:159], v156 offset:3072
	ds_read_b128 v[160:163], v172
	ds_read_b128 v[164:167], v172 offset:1024
	ds_read_b128 v[168:171], v172 offset:2048
	ds_read_b128 v[190:193], v172 offset:3072
	v_lshl_add_u64 v[172:173], s[18:19], 0, v[136:137]
	s_add_i32 m0, s31, 0xc000
	ds_read_b128 v[194:197], v147
	ds_read_b128 v[198:201], v147 offset:1024
	ds_read_b128 v[202:205], v147 offset:2048
	ds_read_b128 v[206:209], v147 offset:3072
	ds_read_b128 v[228:231], v147 offset:4096
	ds_read_b128 v[232:235], v147 offset:5120
	ds_read_b128 v[236:239], v147 offset:6144
	ds_read_b128 v[240:243], v147 offset:7168
	global_load_lds_dwordx4 v[172:173], off
	v_lshl_add_u64 v[172:173], s[18:19], 0, v[138:139]
	s_add_i32 m0, s31, 0xe000
	s_nop 0
	global_load_lds_dwordx4 v[172:173], off
	s_cmp_eq_u32 s48, -2
	s_cbranch_scc1 .Lz0_0_0
	s_waitcnt vmcnt(8)
	s_waitcnt lgkmcnt(0)
	s_barrier
	v_mfma_f32_16x16x32_bf16 v[126:129], v[140:143], v[194:197], v[126:129]
	v_mfma_f32_16x16x32_bf16 v[126:129], v[148:151], v[198:201], v[126:129]
	v_mfma_f32_16x16x32_bf16 v[118:121], v[148:151], v[206:209], v[118:121]
	v_mfma_f32_16x16x32_bf16 v[118:121], v[140:143], v[202:205], v[118:121]
	v_mfma_f32_16x16x32_bf16 v[102:105], v[140:143], v[228:231], v[102:105]
	v_mfma_f32_16x16x32_bf16 v[102:105], v[148:151], v[232:235], v[102:105]
	v_mfma_f32_16x16x32_bf16 v[86:89], v[148:151], v[240:243], v[86:89]
	v_mfma_f32_16x16x32_bf16 v[86:89], v[140:143], v[236:239], v[86:89]
	v_mfma_f32_16x16x32_bf16 v[78:81], v[152:155], v[236:239], v[78:81]
	v_mfma_f32_16x16x32_bf16 v[78:81], v[156:159], v[240:243], v[78:81]
	v_mfma_f32_16x16x32_bf16 v[94:97], v[156:159], v[232:235], v[94:97]
	v_mfma_f32_16x16x32_bf16 v[94:97], v[152:155], v[228:231], v[94:97]
	v_mfma_f32_16x16x32_bf16 v[110:113], v[152:155], v[202:205], v[110:113]
	v_mfma_f32_16x16x32_bf16 v[110:113], v[156:159], v[206:209], v[110:113]
	v_mfma_f32_16x16x32_bf16 v[122:125], v[156:159], v[198:201], v[122:125]
	v_mfma_f32_16x16x32_bf16 v[122:125], v[152:155], v[194:197], v[122:125]
	v_mfma_f32_16x16x32_bf16 v[114:117], v[160:163], v[194:197], v[114:117]
	v_mfma_f32_16x16x32_bf16 v[114:117], v[164:167], v[198:201], v[114:117]
	v_mfma_f32_16x16x32_bf16 v[98:101], v[164:167], v[206:209], v[98:101]
	v_mfma_f32_16x16x32_bf16 v[98:101], v[160:163], v[202:205], v[98:101]
	v_mfma_f32_16x16x32_bf16 v[82:85], v[160:163], v[228:231], v[82:85]
	v_mfma_f32_16x16x32_bf16 v[82:85], v[164:167], v[232:235], v[82:85]
	v_mfma_f32_16x16x32_bf16 v[70:73], v[164:167], v[240:243], v[70:73]
	v_mfma_f32_16x16x32_bf16 v[70:73], v[160:163], v[236:239], v[70:73]
	v_mfma_f32_16x16x32_bf16 v[66:69], v[168:171], v[236:239], v[66:69]
	v_mfma_f32_16x16x32_bf16 v[66:69], v[190:193], v[240:243], v[66:69]
	v_mfma_f32_16x16x32_bf16 v[74:77], v[190:193], v[232:235], v[74:77]
	v_mfma_f32_16x16x32_bf16 v[74:77], v[168:171], v[228:231], v[74:77]
	v_mfma_f32_16x16x32_bf16 v[90:93], v[168:171], v[202:205], v[90:93]
	v_mfma_f32_16x16x32_bf16 v[90:93], v[190:193], v[206:209], v[90:93]
	v_mfma_f32_16x16x32_bf16 v[106:109], v[190:193], v[198:201], v[106:109]
	v_mfma_f32_16x16x32_bf16 v[106:109], v[168:171], v[194:197], v[106:109]
	s_barrier
.Lz0_0_0_ret:
	s_add_i32 s49, s49, s26
	v_lshl_add_u64 v[172:173], s[22:23], 0, v[0:1]
	s_mov_b32 m0, s49
	s_nop 0
	global_load_lds_dwordx4 v[172:173], off
	ds_read_b128 v[194:197], v147 offset:16384
	ds_read_b128 v[198:201], v147 offset:17408
	s_add_i32 m0, s49, 0x2000
	s_add_u32 s50, s22, 0x100000
	v_lshl_add_u64 v[178:179], s[22:23], 0, v[130:131]
	s_addc_u32 s51, s23, 0
	s_add_i32 s49, s52, s26
	global_load_lds_dwordx4 v[178:179], off
	ds_read_b128 v[202:205], v147 offset:18432
	ds_read_b128 v[206:209], v147 offset:19456
	v_lshl_add_u64 v[180:181], s[50:51], 0, v[0:1]
	s_mov_b32 m0, s49
	v_lshl_add_u64 v[210:211], s[24:25], 0, v[132:133]
	global_load_lds_dwordx4 v[180:181], off
	ds_read_b128 v[228:231], v147 offset:20480
	ds_read_b128 v[232:235], v147 offset:21504
	v_lshl_add_u64 v[180:181], s[50:51], 0, v[130:131]
	s_add_i32 m0, s49, 0x2000
	s_nop 0
	global_load_lds_dwordx4 v[180:181], off
	ds_read_b128 v[236:239], v147 offset:22528
	ds_read_b128 v[240:243], v147 offset:23552
	v_lshl_add_u64 v[180:181], s[24:25], 0, v[134:135]
	s_mov_b32 m0, s31
	s_nop 0
	global_load_lds_dwordx4 v[180:181], off
	s_mov_b32 m0, s36
	s_nop 0
	global_load_lds_dwordx4 v[210:211], off
	s_cmp_eq_u32 s48, -2
	s_cbranch_scc1 .Lz0_0_1
	s_waitcnt vmcnt(8)
	s_waitcnt lgkmcnt(0)
	s_barrier
	v_mfma_f32_16x16x32_bf16 v[62:65], v[140:143], v[194:197], v[62:65]
	v_mfma_f32_16x16x32_bf16 v[62:65], v[148:151], v[198:201], v[62:65]
	v_mfma_f32_16x16x32_bf16 v[54:57], v[148:151], v[206:209], v[54:57]
	v_mfma_f32_16x16x32_bf16 v[54:57], v[140:143], v[202:205], v[54:57]
	v_mfma_f32_16x16x32_bf16 v[38:41], v[140:143], v[228:231], v[38:41]
	v_mfma_f32_16x16x32_bf16 v[38:41], v[148:151], v[232:235], v[38:41]
	v_mfma_f32_16x16x32_bf16 v[22:25], v[148:151], v[240:243], v[22:25]
	v_mfma_f32_16x16x32_bf16 v[22:25], v[140:143], v[236:239], v[22:25]
	v_mfma_f32_16x16x32_bf16 v[14:17], v[152:155], v[236:239], v[14:17]
	v_mfma_f32_16x16x32_bf16 v[14:17], v[156:159], v[240:243], v[14:17]
	v_mfma_f32_16x16x32_bf16 v[30:33], v[156:159], v[232:235], v[30:33]
	v_mfma_f32_16x16x32_bf16 v[30:33], v[152:155], v[228:231], v[30:33]
	v_mfma_f32_16x16x32_bf16 v[46:49], v[152:155], v[202:205], v[46:49]
	v_mfma_f32_16x16x32_bf16 v[46:49], v[156:159], v[206:209], v[46:49]
	v_mfma_f32_16x16x32_bf16 v[58:61], v[156:159], v[198:201], v[58:61]
	v_mfma_f32_16x16x32_bf16 v[58:61], v[152:155], v[194:197], v[58:61]
	v_mfma_f32_16x16x32_bf16 v[50:53], v[160:163], v[194:197], v[50:53]
	v_mfma_f32_16x16x32_bf16 v[50:53], v[164:167], v[198:201], v[50:53]
	v_mfma_f32_16x16x32_bf16 v[34:37], v[164:167], v[206:209], v[34:37]
	v_mfma_f32_16x16x32_bf16 v[34:37], v[160:163], v[202:205], v[34:37]
	v_mfma_f32_16x16x32_bf16 v[18:21], v[160:163], v[228:231], v[18:21]
	v_mfma_f32_16x16x32_bf16 v[18:21], v[164:167], v[232:235], v[18:21]
	v_mfma_f32_16x16x32_bf16 v[6:9], v[164:167], v[240:243], v[6:9]
	v_mfma_f32_16x16x32_bf16 v[6:9], v[160:163], v[236:239], v[6:9]
	v_mfma_f32_16x16x32_bf16 v[2:5], v[168:171], v[236:239], v[2:5]
	v_mfma_f32_16x16x32_bf16 v[2:5], v[190:193], v[240:243], v[2:5]
	v_mfma_f32_16x16x32_bf16 v[10:13], v[190:193], v[232:235], v[10:13]
	v_mfma_f32_16x16x32_bf16 v[10:13], v[168:171], v[228:231], v[10:13]
	v_mfma_f32_16x16x32_bf16 v[26:29], v[168:171], v[202:205], v[26:29]
	v_mfma_f32_16x16x32_bf16 v[26:29], v[190:193], v[206:209], v[26:29]
	v_mfma_f32_16x16x32_bf16 v[42:45], v[190:193], v[198:201], v[42:45]
	v_mfma_f32_16x16x32_bf16 v[42:45], v[168:171], v[194:197], v[42:45]
	s_barrier
.Lz0_0_1_ret:
	s_add_i32 s49, 0, 0x18000
	s_add_i32 s50, 0, 0x1c000
	v_add_u32_e32 v156, s49, v145
	v_add_u32_e32 v175, s50, v145
	ds_read_b128 v[140:143], v156
	ds_read_b128 v[148:151], v156 offset:1024
	ds_read_b128 v[152:155], v156 offset:2048
	ds_read_b128 v[156:159], v156 offset:3072
	ds_read_b128 v[160:163], v175
	ds_read_b128 v[164:167], v175 offset:1024
	ds_read_b128 v[168:171], v175 offset:2048
	ds_read_b128 v[190:193], v175 offset:3072
	s_add_u32 s24, s24, 0x100000
	s_addc_u32 s25, s25, 0
	s_mov_b32 m0, s37
	v_lshl_add_u64 v[244:245], s[24:25], 0, v[134:135]
	ds_read_b128 v[194:197], v147 offset:32768
	ds_read_b128 v[198:201], v147 offset:33792
	ds_read_b128 v[202:205], v147 offset:34816
	ds_read_b128 v[206:209], v147 offset:35840
	ds_read_b128 v[228:231], v147 offset:36864
	ds_read_b128 v[232:235], v147 offset:37888
	ds_read_b128 v[236:239], v147 offset:38912
	ds_read_b128 v[240:243], v147 offset:39936
	global_load_lds_dwordx4 v[244:245], off
	v_lshl_add_u64 v[244:245], s[24:25], 0, v[132:133]
	s_mov_b32 m0, s38
	s_nop 0
	global_load_lds_dwordx4 v[244:245], off
	s_waitcnt vmcnt(8)
	s_waitcnt lgkmcnt(0)
	s_barrier
	v_mfma_f32_16x16x32_bf16 v[126:129], v[140:143], v[194:197], v[126:129]
	v_mfma_f32_16x16x32_bf16 v[126:129], v[148:151], v[198:201], v[126:129]
	v_mfma_f32_16x16x32_bf16 v[118:121], v[148:151], v[206:209], v[118:121]
	v_mfma_f32_16x16x32_bf16 v[118:121], v[140:143], v[202:205], v[118:121]
	v_mfma_f32_16x16x32_bf16 v[102:105], v[140:143], v[228:231], v[102:105]
	v_mfma_f32_16x16x32_bf16 v[102:105], v[148:151], v[232:235], v[102:105]
	v_mfma_f32_16x16x32_bf16 v[86:89], v[148:151], v[240:243], v[86:89]
	v_mfma_f32_16x16x32_bf16 v[86:89], v[140:143], v[236:239], v[86:89]
	v_mfma_f32_16x16x32_bf16 v[78:81], v[152:155], v[236:239], v[78:81]
	v_mfma_f32_16x16x32_bf16 v[78:81], v[156:159], v[240:243], v[78:81]
	v_mfma_f32_16x16x32_bf16 v[94:97], v[156:159], v[232:235], v[94:97]
	v_mfma_f32_16x16x32_bf16 v[94:97], v[152:155], v[228:231], v[94:97]
	v_mfma_f32_16x16x32_bf16 v[110:113], v[152:155], v[202:205], v[110:113]
	v_mfma_f32_16x16x32_bf16 v[110:113], v[156:159], v[206:209], v[110:113]
	v_mfma_f32_16x16x32_bf16 v[122:125], v[156:159], v[198:201], v[122:125]
	v_mfma_f32_16x16x32_bf16 v[122:125], v[152:155], v[194:197], v[122:125]
	v_mfma_f32_16x16x32_bf16 v[114:117], v[160:163], v[194:197], v[114:117]
	v_mfma_f32_16x16x32_bf16 v[114:117], v[164:167], v[198:201], v[114:117]
	v_mfma_f32_16x16x32_bf16 v[98:101], v[164:167], v[206:209], v[98:101]
	v_mfma_f32_16x16x32_bf16 v[98:101], v[160:163], v[202:205], v[98:101]
	v_mfma_f32_16x16x32_bf16 v[82:85], v[160:163], v[228:231], v[82:85]
	v_mfma_f32_16x16x32_bf16 v[82:85], v[164:167], v[232:235], v[82:85]
	v_mfma_f32_16x16x32_bf16 v[70:73], v[164:167], v[240:243], v[70:73]
	v_mfma_f32_16x16x32_bf16 v[70:73], v[160:163], v[236:239], v[70:73]
	v_mfma_f32_16x16x32_bf16 v[66:69], v[168:171], v[236:239], v[66:69]
	v_mfma_f32_16x16x32_bf16 v[66:69], v[190:193], v[240:243], v[66:69]
	v_mfma_f32_16x16x32_bf16 v[74:77], v[190:193], v[232:235], v[74:77]
	v_mfma_f32_16x16x32_bf16 v[74:77], v[168:171], v[228:231], v[74:77]
	v_mfma_f32_16x16x32_bf16 v[90:93], v[168:171], v[202:205], v[90:93]
	v_mfma_f32_16x16x32_bf16 v[90:93], v[190:193], v[206:209], v[90:93]
	v_mfma_f32_16x16x32_bf16 v[106:109], v[190:193], v[198:201], v[106:109]
	v_mfma_f32_16x16x32_bf16 v[106:109], v[168:171], v[194:197], v[106:109]
	s_barrier
	s_add_i32 s24, s49, s26
	v_lshl_add_u64 v[172:173], v[172:173], 0, s[34:35]
	s_mov_b32 m0, s24
	s_nop 0
	global_load_lds_dwordx4 v[172:173], off
	ds_read_b128 v[194:197], v147 offset:49152
	ds_read_b128 v[198:201], v147 offset:50176
	s_add_i32 m0, s24, 0x2000
	s_add_u32 s22, s22, 0x100080
	v_lshl_add_u64 v[172:173], v[178:179], 0, s[34:35]
	s_addc_u32 s23, s23, 0
	s_add_i32 s24, s50, s26
	global_load_lds_dwordx4 v[172:173], off
	ds_read_b128 v[202:205], v147 offset:51200
	ds_read_b128 v[206:209], v147 offset:52224
	v_lshl_add_u64 v[172:173], s[22:23], 0, v[0:1]
	s_mov_b32 m0, s24
	s_nop 0
	global_load_lds_dwordx4 v[172:173], off
	ds_read_b128 v[228:231], v147 offset:53248
	ds_read_b128 v[232:235], v147 offset:54272
	v_lshl_add_u64 v[172:173], s[22:23], 0, v[130:131]
	s_add_i32 m0, s24, 0x2000
	s_nop 0
	global_load_lds_dwordx4 v[172:173], off
	ds_read_b128 v[236:239], v147 offset:55296
	ds_read_b128 v[240:243], v147 offset:56320
	v_lshl_add_u64 v[172:173], v[180:181], 0, s[34:35]
	s_mov_b32 m0, s39
	s_nop 0
	global_load_lds_dwordx4 v[172:173], off
	s_add_i32 s48, s48, 2
	s_add_u32 s18, s18, 0x100
	s_addc_u32 s19, s19, 0
	s_add_u32 s46, s46, 0x100
	s_addc_u32 s47, s47, 0
	s_add_u32 s22, s18, 0xfff00080
	s_addc_u32 s23, s19, -1
	s_cmp_eq_u32 s48, 60
	s_cselect_b32 s25, s9, s23
	s_cselect_b32 s24, s44, s22
	s_cselect_b32 s23, s7, s47
	s_cselect_b32 s22, s45, s46
	v_lshl_add_u64 v[172:173], v[210:211], 0, s[34:35]
	s_mov_b32 m0, s40
	s_nop 0
	global_load_lds_dwordx4 v[172:173], off
	s_waitcnt vmcnt(8)
	s_waitcnt lgkmcnt(0)
	s_barrier
	v_mfma_f32_16x16x32_bf16 v[62:65], v[140:143], v[194:197], v[62:65]
	v_mfma_f32_16x16x32_bf16 v[62:65], v[148:151], v[198:201], v[62:65]
	v_mfma_f32_16x16x32_bf16 v[54:57], v[148:151], v[206:209], v[54:57]
	v_mfma_f32_16x16x32_bf16 v[54:57], v[140:143], v[202:205], v[54:57]
	v_mfma_f32_16x16x32_bf16 v[38:41], v[140:143], v[228:231], v[38:41]
	v_mfma_f32_16x16x32_bf16 v[38:41], v[148:151], v[232:235], v[38:41]
	v_mfma_f32_16x16x32_bf16 v[22:25], v[148:151], v[240:243], v[22:25]
	v_mfma_f32_16x16x32_bf16 v[22:25], v[140:143], v[236:239], v[22:25]
	v_mfma_f32_16x16x32_bf16 v[14:17], v[152:155], v[236:239], v[14:17]
	v_mfma_f32_16x16x32_bf16 v[14:17], v[156:159], v[240:243], v[14:17]
	v_mfma_f32_16x16x32_bf16 v[30:33], v[156:159], v[232:235], v[30:33]
	v_mfma_f32_16x16x32_bf16 v[30:33], v[152:155], v[228:231], v[30:33]
	v_mfma_f32_16x16x32_bf16 v[46:49], v[152:155], v[202:205], v[46:49]
	v_mfma_f32_16x16x32_bf16 v[46:49], v[156:159], v[206:209], v[46:49]
	v_mfma_f32_16x16x32_bf16 v[58:61], v[156:159], v[198:201], v[58:61]
	v_mfma_f32_16x16x32_bf16 v[58:61], v[152:155], v[194:197], v[58:61]
	v_mfma_f32_16x16x32_bf16 v[50:53], v[160:163], v[194:197], v[50:53]
	v_mfma_f32_16x16x32_bf16 v[50:53], v[164:167], v[198:201], v[50:53]
	v_mfma_f32_16x16x32_bf16 v[34:37], v[164:167], v[206:209], v[34:37]
	v_mfma_f32_16x16x32_bf16 v[34:37], v[160:163], v[202:205], v[34:37]
	v_mfma_f32_16x16x32_bf16 v[18:21], v[160:163], v[228:231], v[18:21]
	v_mfma_f32_16x16x32_bf16 v[18:21], v[164:167], v[232:235], v[18:21]
	v_mfma_f32_16x16x32_bf16 v[6:9], v[164:167], v[240:243], v[6:9]
	v_mfma_f32_16x16x32_bf16 v[6:9], v[160:163], v[236:239], v[6:9]
	v_mfma_f32_16x16x32_bf16 v[2:5], v[168:171], v[236:239], v[2:5]
	v_mfma_f32_16x16x32_bf16 v[2:5], v[190:193], v[240:243], v[2:5]
	v_mfma_f32_16x16x32_bf16 v[10:13], v[190:193], v[232:235], v[10:13]
	v_mfma_f32_16x16x32_bf16 v[10:13], v[168:171], v[228:231], v[10:13]
	v_mfma_f32_16x16x32_bf16 v[26:29], v[168:171], v[202:205], v[26:29]
	v_mfma_f32_16x16x32_bf16 v[26:29], v[190:193], v[206:209], v[26:29]
	v_mfma_f32_16x16x32_bf16 v[42:45], v[190:193], v[198:201], v[42:45]
	v_mfma_f32_16x16x32_bf16 v[42:45], v[168:171], v[194:197], v[42:45]
	s_barrier
	s_cmp_gt_u32 s48, 61
	s_cbranch_scc0 .LBB0_139
	s_and_b64 vcc, exec, s[4:5]
	s_cbranch_vccz .LBB0_142
	s_barrier

.Lz0_0_0:
	s_waitcnt vmcnt(8)
	s_waitcnt lgkmcnt(0)
	s_barrier
	v_mfma_f32_16x16x32_bf16 v[126:129], v[140:143], v[194:197], 0
	v_mfma_f32_16x16x32_bf16 v[126:129], v[148:151], v[198:201], v[126:129]
	v_mfma_f32_16x16x32_bf16 v[118:121], v[148:151], v[206:209], 0
	v_mfma_f32_16x16x32_bf16 v[118:121], v[140:143], v[202:205], v[118:121]
	v_mfma_f32_16x16x32_bf16 v[102:105], v[140:143], v[228:231], 0
	v_mfma_f32_16x16x32_bf16 v[102:105], v[148:151], v[232:235], v[102:105]
	v_mfma_f32_16x16x32_bf16 v[86:89], v[148:151], v[240:243], 0
	v_mfma_f32_16x16x32_bf16 v[86:89], v[140:143], v[236:239], v[86:89]
	v_mfma_f32_16x16x32_bf16 v[78:81], v[152:155], v[236:239], 0
	v_mfma_f32_16x16x32_bf16 v[78:81], v[156:159], v[240:243], v[78:81]
	v_mfma_f32_16x16x32_bf16 v[94:97], v[156:159], v[232:235], 0
	v_mfma_f32_16x16x32_bf16 v[94:97], v[152:155], v[228:231], v[94:97]
	v_mfma_f32_16x16x32_bf16 v[110:113], v[152:155], v[202:205], 0
	v_mfma_f32_16x16x32_bf16 v[110:113], v[156:159], v[206:209], v[110:113]
	v_mfma_f32_16x16x32_bf16 v[122:125], v[156:159], v[198:201], 0
	v_mfma_f32_16x16x32_bf16 v[122:125], v[152:155], v[194:197], v[122:125]
	v_mfma_f32_16x16x32_bf16 v[114:117], v[160:163], v[194:197], 0
	v_mfma_f32_16x16x32_bf16 v[114:117], v[164:167], v[198:201], v[114:117]
	v_mfma_f32_16x16x32_bf16 v[98:101], v[164:167], v[206:209], 0
	v_mfma_f32_16x16x32_bf16 v[98:101], v[160:163], v[202:205], v[98:101]
	v_mfma_f32_16x16x32_bf16 v[82:85], v[160:163], v[228:231], 0
	v_mfma_f32_16x16x32_bf16 v[82:85], v[164:167], v[232:235], v[82:85]
	v_mfma_f32_16x16x32_bf16 v[70:73], v[164:167], v[240:243], 0
	v_mfma_f32_16x16x32_bf16 v[70:73], v[160:163], v[236:239], v[70:73]
	v_mfma_f32_16x16x32_bf16 v[66:69], v[168:171], v[236:239], 0
	v_mfma_f32_16x16x32_bf16 v[66:69], v[190:193], v[240:243], v[66:69]
	v_mfma_f32_16x16x32_bf16 v[74:77], v[190:193], v[232:235], 0
	v_mfma_f32_16x16x32_bf16 v[74:77], v[168:171], v[228:231], v[74:77]
	v_mfma_f32_16x16x32_bf16 v[90:93], v[168:171], v[202:205], 0
	v_mfma_f32_16x16x32_bf16 v[90:93], v[190:193], v[206:209], v[90:93]
	v_mfma_f32_16x16x32_bf16 v[106:109], v[190:193], v[198:201], 0
	v_mfma_f32_16x16x32_bf16 v[106:109], v[168:171], v[194:197], v[106:109]
	s_barrier
	s_branch .Lz0_0_0_ret
.Lz0_0_1:
	s_waitcnt vmcnt(8)
	s_waitcnt lgkmcnt(0)
	s_barrier
	v_mfma_f32_16x16x32_bf16 v[62:65], v[140:143], v[194:197], 0
	v_mfma_f32_16x16x32_bf16 v[62:65], v[148:151], v[198:201], v[62:65]
	v_mfma_f32_16x16x32_bf16 v[54:57], v[148:151], v[206:209], 0
	v_mfma_f32_16x16x32_bf16 v[54:57], v[140:143], v[202:205], v[54:57]
	v_mfma_f32_16x16x32_bf16 v[38:41], v[140:143], v[228:231], 0
	v_mfma_f32_16x16x32_bf16 v[38:41], v[148:151], v[232:235], v[38:41]
	v_mfma_f32_16x16x32_bf16 v[22:25], v[148:151], v[240:243], 0
	v_mfma_f32_16x16x32_bf16 v[22:25], v[140:143], v[236:239], v[22:25]
	v_mfma_f32_16x16x32_bf16 v[14:17], v[152:155], v[236:239], 0
	v_mfma_f32_16x16x32_bf16 v[14:17], v[156:159], v[240:243], v[14:17]
	v_mfma_f32_16x16x32_bf16 v[30:33], v[156:159], v[232:235], 0
	v_mfma_f32_16x16x32_bf16 v[30:33], v[152:155], v[228:231], v[30:33]
	v_mfma_f32_16x16x32_bf16 v[46:49], v[152:155], v[202:205], 0
	v_mfma_f32_16x16x32_bf16 v[46:49], v[156:159], v[206:209], v[46:49]
	v_mfma_f32_16x16x32_bf16 v[58:61], v[156:159], v[198:201], 0
	v_mfma_f32_16x16x32_bf16 v[58:61], v[152:155], v[194:197], v[58:61]
	v_mfma_f32_16x16x32_bf16 v[50:53], v[160:163], v[194:197], 0
	v_mfma_f32_16x16x32_bf16 v[50:53], v[164:167], v[198:201], v[50:53]
	v_mfma_f32_16x16x32_bf16 v[34:37], v[164:167], v[206:209], 0
	v_mfma_f32_16x16x32_bf16 v[34:37], v[160:163], v[202:205], v[34:37]
	v_mfma_f32_16x16x32_bf16 v[18:21], v[160:163], v[228:231], 0
	v_mfma_f32_16x16x32_bf16 v[18:21], v[164:167], v[232:235], v[18:21]
	v_mfma_f32_16x16x32_bf16 v[6:9], v[164:167], v[240:243], 0
	v_mfma_f32_16x16x32_bf16 v[6:9], v[160:163], v[236:239], v[6:9]
	v_mfma_f32_16x16x32_bf16 v[2:5], v[168:171], v[236:239], 0
	v_mfma_f32_16x16x32_bf16 v[2:5], v[190:193], v[240:243], v[2:5]
	v_mfma_f32_16x16x32_bf16 v[10:13], v[190:193], v[232:235], 0
	v_mfma_f32_16x16x32_bf16 v[10:13], v[168:171], v[228:231], v[10:13]
	v_mfma_f32_16x16x32_bf16 v[26:29], v[168:171], v[202:205], 0
	v_mfma_f32_16x16x32_bf16 v[26:29], v[190:193], v[206:209], v[26:29]
	v_mfma_f32_16x16x32_bf16 v[42:45], v[190:193], v[198:201], 0
	v_mfma_f32_16x16x32_bf16 v[42:45], v[168:171], v[194:197], v[42:45]
	s_barrier
	s_branch .Lz0_0_1_ret

.LBB0_561:
	s_andn2_b64 vcc, exec, s[0:1]
	v_readlane_b32 s0, v253, 15
	v_readlane_b32 s1, v253, 16
	s_nop 1
	v_cndmask_b32_e64 v0, 0, 1, s[0:1]
	v_cmp_ne_u32_e64 s[36:37], 1, v0
	s_cbranch_vccnz .LBB0_634
	v_readlane_b32 s0, v251, 21
	s_and_b64 vcc, exec, s[36:37]
	s_waitcnt vmcnt(0)
	v_mbcnt_lo_u32_b32 v3, -1, 0
	v_mbcnt_hi_u32_b32 v3, -1, v3
	s_cbranch_vccnz .LBB0_582
	v_readlane_b32 s1, v255, 31
	s_add_u32 s26, s1, 0x5200000
	v_readlane_b32 s1, v255, 32
	s_addc_u32 s31, s1, 0
	s_lshl_b32 s38, s0, 10
	v_lshl_add_u32 v0, v3, 4, s38
	s_waitcnt vmcnt(0)
	v_add_u32_e32 v4, 0x2000, v0
	v_ashrrev_i32_e32 v2, 31, v4
	v_lshrrev_b32_e32 v2, 22, v2
	v_add_u32_e32 v2, v4, v2
	v_ashrrev_i32_e32 v2, 10, v2
	v_mul_i32_i24_e32 v5, 0x400, v2
	v_sub_u32_e32 v4, v4, v5
	v_lshrrev_b32_e32 v5, 4, v4
	v_bitop3_b32 v5, v5, v4, 32 bitop3:0x6c
	v_ashrrev_i32_e32 v4, 31, v5
	v_lshrrev_b32_e32 v4, 26, v4
	v_add_u32_e32 v6, v5, v4
	v_ashrrev_i32_e32 v4, 6, v6
	v_lshlrev_b32_e32 v7, 3, v2
	v_and_b32_e32 v6, 0xffc0, v6
	v_and_b32_e32 v7, -16, v7
	v_sub_u32_e32 v5, v5, v6
	v_add_u32_e32 v7, v4, v7
	v_lshrrev_b16_e32 v6, 7, v5
	v_and_b32_e32 v8, 3, v4
	s_mov_b32 s2, 0x7ffe0
	v_lshrrev_b32_e32 v9, 2, v7
	v_lshlrev_b32_e32 v10, 1, v7
	v_and_b32_e32 v6, 1, v6
	v_and_or_b32 v8, v7, s2, v8
	v_and_b32_e32 v9, 4, v9
	v_and_b32_e32 v10, 24, v10
	v_add_u16_e32 v5, v5, v6
	v_or3_b32 v8, v8, v9, v10
	v_lshlrev_b32_e32 v9, 5, v2
	v_ashrrev_i16_sdwa v5, v212, sext(v5) dst_sel:DWORD dst_unused:UNUSED_PAD src0_sel:DWORD src1_sel:BYTE_0
	v_and_b32_e32 v9, 32, v9
	v_bfe_i32 v5, v5, 0, 16
	v_add_lshl_u32 v6, v9, v5, 1
	v_lshl_add_u32 v130, v8, 13, v6
	v_lshl_add_u32 v132, v7, 13, v6
	v_ashrrev_i32_e32 v6, 31, v0
	v_lshrrev_b32_e32 v6, 22, v6
	v_add_u32_e32 v6, v0, v6
	v_ashrrev_i32_e32 v6, 10, v6
	v_mul_i32_i24_e32 v7, 0x400, v6
	v_sub_u32_e32 v0, v0, v7
	v_lshrrev_b32_e32 v7, 4, v0
	v_bitop3_b32 v0, v7, v0, 32 bitop3:0x6c
	v_ashrrev_i32_e32 v7, 31, v0
	v_lshrrev_b32_e32 v7, 26, v7
	v_add_u32_e32 v8, v0, v7
	v_lshlrev_b32_e32 v9, 3, v6
	v_ashrrev_i32_e32 v7, 6, v8
	v_and_b32_e32 v9, -16, v9
	v_add_u32_e32 v9, v7, v9
	v_and_b32_e32 v10, 3, v7
	v_lshrrev_b32_e32 v11, 2, v9
	v_lshlrev_b32_e32 v12, 1, v9
	v_and_b32_e32 v8, 0xc0, v8
	v_and_or_b32 v10, v9, s2, v10
	v_and_b32_e32 v11, 4, v11
	v_and_b32_e32 v12, 24, v12
	v_sub_u32_e32 v0, v0, v8
	s_ashr_i32 s1, s0, 2
	v_or3_b32 v10, v10, v11, v12
	v_lshlrev_b32_e32 v11, 5, v6
	v_ashrrev_i16_sdwa v0, v212, sext(v0) dst_sel:DWORD dst_unused:UNUSED_PAD src0_sel:DWORD src1_sel:BYTE_0
	v_readlane_b32 s2, v254, 13
	v_and_b32_e32 v11, 32, v11
	v_bfe_i32 v8, v0, 0, 16
	v_readlane_b32 s3, v254, 14
	s_add_u32 s22, s26, s2
	v_add_lshl_u32 v11, v11, v8, 1
	s_addc_u32 s23, s31, s3
	s_add_i32 s39, s38, 0
	v_lshl_add_u32 v0, v10, 13, v11
	s_add_i32 m0, s39, 0x10000
	v_lshl_add_u32 v134, v9, 13, v11
	global_load_lds_dwordx4 v0, s[22:23]
	s_add_i32 m0, s39, 0x12000
	s_add_u32 s2, s22, 0x100000
	global_load_lds_dwordx4 v130, s[22:23]
	s_addc_u32 s3, s23, 0
	s_add_i32 m0, s39, 0x14000
	s_add_i32 s40, s39, 0x2000
	global_load_lds_dwordx4 v0, s[2:3]
	s_add_i32 m0, s39, 0x16000
	s_add_i32 s41, s39, 0x4000
	global_load_lds_dwordx4 v130, s[2:3]
	v_readlane_b32 s2, v254, 17
	s_mov_b32 m0, s39
	v_readlane_b32 s3, v254, 18
	s_add_i32 s42, s39, 0x6000
	s_cmp_eq_u32 s1, 1
	s_nop 2
	global_load_lds_dwordx4 v134, s[2:3]
	s_mov_b32 m0, s40
	s_nop 0
	global_load_lds_dwordx4 v132, s[2:3]
	v_readlane_b32 s2, v254, 19
	s_mov_b32 m0, s41
	v_readlane_b32 s3, v254, 20
	s_nop 4
	global_load_lds_dwordx4 v134, s[2:3]
	s_mov_b32 m0, s42
	s_nop 0
	global_load_lds_dwordx4 v132, s[2:3]
	s_cselect_b64 s[2:3], -1, 0
	s_cmp_lg_u32 s1, 1
	s_cbranch_scc1 .LBB0_565
	s_barrier
	s_setprio 1

.LBB0_575:
	s_add_i32 s53, 0, 0x10000
	v_add_u32_e32 v140, s53, v143
	s_add_i32 s56, 0, 0x14000
	ds_read_b128 v[146:149], v140
	ds_read_b128 v[150:153], v140 offset:1024
	ds_read_b128 v[154:157], v140 offset:2048
	ds_read_b128 v[158:161], v140 offset:3072
	v_add_u32_e32 v140, s56, v143
	ds_read_b128 v[162:165], v140
	ds_read_b128 v[166:169], v140 offset:1024
	ds_read_b128 v[170:173], v140 offset:2048
	ds_read_b128 v[178:181], v140 offset:3072
	v_lshl_add_u64 v[140:141], s[18:19], 0, v[136:137]
	s_add_i32 m0, s39, 0xc000
	ds_read_b128 v[190:193], v145
	ds_read_b128 v[194:197], v145 offset:1024
	ds_read_b128 v[198:201], v145 offset:2048
	ds_read_b128 v[202:205], v145 offset:3072
	ds_read_b128 v[206:209], v145 offset:4096
	ds_read_b128 v[228:231], v145 offset:5120
	ds_read_b128 v[232:235], v145 offset:6144
	ds_read_b128 v[236:239], v145 offset:7168
	global_load_lds_dwordx4 v[140:141], off
	v_lshl_add_u64 v[140:141], s[18:19], 0, v[138:139]
	s_add_i32 m0, s39, 0xe000
	s_nop 0
	global_load_lds_dwordx4 v[140:141], off
	s_cmp_eq_u32 s52, -2
	s_cbranch_scc1 .Lz0_1_0
	s_waitcnt vmcnt(8)
	s_waitcnt lgkmcnt(0)
	s_barrier
	v_mfma_f32_16x16x32_bf16 v[126:129], v[146:149], v[190:193], v[126:129]
	v_mfma_f32_16x16x32_bf16 v[126:129], v[150:153], v[194:197], v[126:129]
	v_mfma_f32_16x16x32_bf16 v[118:121], v[150:153], v[202:205], v[118:121]
	v_mfma_f32_16x16x32_bf16 v[118:121], v[146:149], v[198:201], v[118:121]
	v_mfma_f32_16x16x32_bf16 v[102:105], v[146:149], v[206:209], v[102:105]
	v_mfma_f32_16x16x32_bf16 v[102:105], v[150:153], v[228:231], v[102:105]
	v_mfma_f32_16x16x32_bf16 v[86:89], v[150:153], v[236:239], v[86:89]
	v_mfma_f32_16x16x32_bf16 v[86:89], v[146:149], v[232:235], v[86:89]
	v_mfma_f32_16x16x32_bf16 v[78:81], v[154:157], v[232:235], v[78:81]
	v_mfma_f32_16x16x32_bf16 v[78:81], v[158:161], v[236:239], v[78:81]
	v_mfma_f32_16x16x32_bf16 v[94:97], v[158:161], v[228:231], v[94:97]
	v_mfma_f32_16x16x32_bf16 v[94:97], v[154:157], v[206:209], v[94:97]
	v_mfma_f32_16x16x32_bf16 v[110:113], v[154:157], v[198:201], v[110:113]
	v_mfma_f32_16x16x32_bf16 v[110:113], v[158:161], v[202:205], v[110:113]
	v_mfma_f32_16x16x32_bf16 v[122:125], v[158:161], v[194:197], v[122:125]
	v_mfma_f32_16x16x32_bf16 v[122:125], v[154:157], v[190:193], v[122:125]
	v_mfma_f32_16x16x32_bf16 v[114:117], v[162:165], v[190:193], v[114:117]
	v_mfma_f32_16x16x32_bf16 v[114:117], v[166:169], v[194:197], v[114:117]
	v_mfma_f32_16x16x32_bf16 v[98:101], v[166:169], v[202:205], v[98:101]
	v_mfma_f32_16x16x32_bf16 v[98:101], v[162:165], v[198:201], v[98:101]
	v_mfma_f32_16x16x32_bf16 v[82:85], v[162:165], v[206:209], v[82:85]
	v_mfma_f32_16x16x32_bf16 v[82:85], v[166:169], v[228:231], v[82:85]
	v_mfma_f32_16x16x32_bf16 v[70:73], v[166:169], v[236:239], v[70:73]
	v_mfma_f32_16x16x32_bf16 v[70:73], v[162:165], v[232:235], v[70:73]
	v_mfma_f32_16x16x32_bf16 v[66:69], v[170:173], v[232:235], v[66:69]
	v_mfma_f32_16x16x32_bf16 v[66:69], v[178:181], v[236:239], v[66:69]
	v_mfma_f32_16x16x32_bf16 v[74:77], v[178:181], v[228:231], v[74:77]
	v_mfma_f32_16x16x32_bf16 v[74:77], v[170:173], v[206:209], v[74:77]
	v_mfma_f32_16x16x32_bf16 v[90:93], v[170:173], v[198:201], v[90:93]
	v_mfma_f32_16x16x32_bf16 v[90:93], v[178:181], v[202:205], v[90:93]
	v_mfma_f32_16x16x32_bf16 v[106:109], v[178:181], v[194:197], v[106:109]
	v_mfma_f32_16x16x32_bf16 v[106:109], v[170:173], v[190:193], v[106:109]
	s_barrier
.Lz0_1_0_ret:
	s_add_i32 s53, s53, s38
	v_lshl_add_u64 v[140:141], s[22:23], 0, v[0:1]
	s_mov_b32 m0, s53
	s_nop 0
	global_load_lds_dwordx4 v[140:141], off
	ds_read_b128 v[190:193], v145 offset:16384
	ds_read_b128 v[194:197], v145 offset:17408
	s_add_i32 m0, s53, 0x2000
	s_add_u32 s54, s22, 0x100000
	v_lshl_add_u64 v[186:187], s[22:23], 0, v[130:131]
	s_addc_u32 s55, s23, 0
	s_add_i32 s53, s56, s38
	global_load_lds_dwordx4 v[186:187], off
	ds_read_b128 v[198:201], v145 offset:18432
	ds_read_b128 v[202:205], v145 offset:19456
	v_lshl_add_u64 v[188:189], s[54:55], 0, v[0:1]
	s_mov_b32 m0, s53
	v_lshl_add_u64 v[210:211], s[24:25], 0, v[132:133]
	global_load_lds_dwordx4 v[188:189], off
	ds_read_b128 v[206:209], v145 offset:20480
	ds_read_b128 v[228:231], v145 offset:21504
	v_lshl_add_u64 v[188:189], s[54:55], 0, v[130:131]
	s_add_i32 m0, s53, 0x2000
	s_nop 0
	global_load_lds_dwordx4 v[188:189], off
	ds_read_b128 v[232:235], v145 offset:22528
	ds_read_b128 v[236:239], v145 offset:23552
	v_lshl_add_u64 v[188:189], s[24:25], 0, v[134:135]
	s_mov_b32 m0, s39
	s_nop 0
	global_load_lds_dwordx4 v[188:189], off
	s_mov_b32 m0, s40
	s_nop 0
	global_load_lds_dwordx4 v[210:211], off
	s_cmp_eq_u32 s52, -2
	s_cbranch_scc1 .Lz0_1_1
	s_waitcnt vmcnt(8)
	s_waitcnt lgkmcnt(0)
	s_barrier
	v_mfma_f32_16x16x32_bf16 v[62:65], v[146:149], v[190:193], v[62:65]
	v_mfma_f32_16x16x32_bf16 v[62:65], v[150:153], v[194:197], v[62:65]
	v_mfma_f32_16x16x32_bf16 v[54:57], v[150:153], v[202:205], v[54:57]
	v_mfma_f32_16x16x32_bf16 v[54:57], v[146:149], v[198:201], v[54:57]
	v_mfma_f32_16x16x32_bf16 v[38:41], v[146:149], v[206:209], v[38:41]
	v_mfma_f32_16x16x32_bf16 v[38:41], v[150:153], v[228:231], v[38:41]
	v_mfma_f32_16x16x32_bf16 v[22:25], v[150:153], v[236:239], v[22:25]
	v_mfma_f32_16x16x32_bf16 v[22:25], v[146:149], v[232:235], v[22:25]
	v_mfma_f32_16x16x32_bf16 v[14:17], v[154:157], v[232:235], v[14:17]
	v_mfma_f32_16x16x32_bf16 v[14:17], v[158:161], v[236:239], v[14:17]
	v_mfma_f32_16x16x32_bf16 v[30:33], v[158:161], v[228:231], v[30:33]
	v_mfma_f32_16x16x32_bf16 v[30:33], v[154:157], v[206:209], v[30:33]
	v_mfma_f32_16x16x32_bf16 v[46:49], v[154:157], v[198:201], v[46:49]
	v_mfma_f32_16x16x32_bf16 v[46:49], v[158:161], v[202:205], v[46:49]
	v_mfma_f32_16x16x32_bf16 v[58:61], v[158:161], v[194:197], v[58:61]
	v_mfma_f32_16x16x32_bf16 v[58:61], v[154:157], v[190:193], v[58:61]
	v_mfma_f32_16x16x32_bf16 v[50:53], v[162:165], v[190:193], v[50:53]
	v_mfma_f32_16x16x32_bf16 v[50:53], v[166:169], v[194:197], v[50:53]
	v_mfma_f32_16x16x32_bf16 v[34:37], v[166:169], v[202:205], v[34:37]
	v_mfma_f32_16x16x32_bf16 v[34:37], v[162:165], v[198:201], v[34:37]
	v_mfma_f32_16x16x32_bf16 v[18:21], v[162:165], v[206:209], v[18:21]
	v_mfma_f32_16x16x32_bf16 v[18:21], v[166:169], v[228:231], v[18:21]
	v_mfma_f32_16x16x32_bf16 v[6:9], v[166:169], v[236:239], v[6:9]
	v_mfma_f32_16x16x32_bf16 v[6:9], v[162:165], v[232:235], v[6:9]
	v_mfma_f32_16x16x32_bf16 v[2:5], v[170:173], v[232:235], v[2:5]
	v_mfma_f32_16x16x32_bf16 v[2:5], v[178:181], v[236:239], v[2:5]
	v_mfma_f32_16x16x32_bf16 v[10:13], v[178:181], v[228:231], v[10:13]
	v_mfma_f32_16x16x32_bf16 v[10:13], v[170:173], v[206:209], v[10:13]
	v_mfma_f32_16x16x32_bf16 v[26:29], v[170:173], v[198:201], v[26:29]
	v_mfma_f32_16x16x32_bf16 v[26:29], v[178:181], v[202:205], v[26:29]
	v_mfma_f32_16x16x32_bf16 v[42:45], v[178:181], v[194:197], v[42:45]
	v_mfma_f32_16x16x32_bf16 v[42:45], v[170:173], v[190:193], v[42:45]
	s_barrier
.Lz0_1_1_ret:
	s_add_i32 s53, 0, 0x18000
	s_add_i32 s54, 0, 0x1c000
	v_add_u32_e32 v158, s53, v143
	v_add_u32_e32 v175, s54, v143
	ds_read_b128 v[146:149], v158
	ds_read_b128 v[150:153], v158 offset:1024
	ds_read_b128 v[154:157], v158 offset:2048
	ds_read_b128 v[158:161], v158 offset:3072
	ds_read_b128 v[162:165], v175
	ds_read_b128 v[166:169], v175 offset:1024
	ds_read_b128 v[170:173], v175 offset:2048
	ds_read_b128 v[178:181], v175 offset:3072
	s_add_u32 s24, s24, 0x100000
	s_addc_u32 s25, s25, 0
	s_mov_b32 m0, s41
	v_lshl_add_u64 v[226:227], s[24:25], 0, v[134:135]
	ds_read_b128 v[190:193], v145 offset:32768
	ds_read_b128 v[194:197], v145 offset:33792
	ds_read_b128 v[198:201], v145 offset:34816
	ds_read_b128 v[202:205], v145 offset:35840
	ds_read_b128 v[206:209], v145 offset:36864
	ds_read_b128 v[228:231], v145 offset:37888
	ds_read_b128 v[232:235], v145 offset:38912
	ds_read_b128 v[236:239], v145 offset:39936
	global_load_lds_dwordx4 v[226:227], off
	v_lshl_add_u64 v[226:227], s[24:25], 0, v[132:133]
	s_mov_b32 m0, s42
	s_nop 0
	global_load_lds_dwordx4 v[226:227], off
	s_waitcnt vmcnt(8)
	s_waitcnt lgkmcnt(0)
	s_barrier
	v_mfma_f32_16x16x32_bf16 v[126:129], v[146:149], v[190:193], v[126:129]
	v_mfma_f32_16x16x32_bf16 v[126:129], v[150:153], v[194:197], v[126:129]
	v_mfma_f32_16x16x32_bf16 v[118:121], v[150:153], v[202:205], v[118:121]
	v_mfma_f32_16x16x32_bf16 v[118:121], v[146:149], v[198:201], v[118:121]
	v_mfma_f32_16x16x32_bf16 v[102:105], v[146:149], v[206:209], v[102:105]
	v_mfma_f32_16x16x32_bf16 v[102:105], v[150:153], v[228:231], v[102:105]
	v_mfma_f32_16x16x32_bf16 v[86:89], v[150:153], v[236:239], v[86:89]
	v_mfma_f32_16x16x32_bf16 v[86:89], v[146:149], v[232:235], v[86:89]
	v_mfma_f32_16x16x32_bf16 v[78:81], v[154:157], v[232:235], v[78:81]
	v_mfma_f32_16x16x32_bf16 v[78:81], v[158:161], v[236:239], v[78:81]
	v_mfma_f32_16x16x32_bf16 v[94:97], v[158:161], v[228:231], v[94:97]
	v_mfma_f32_16x16x32_bf16 v[94:97], v[154:157], v[206:209], v[94:97]
	v_mfma_f32_16x16x32_bf16 v[110:113], v[154:157], v[198:201], v[110:113]
	v_mfma_f32_16x16x32_bf16 v[110:113], v[158:161], v[202:205], v[110:113]
	v_mfma_f32_16x16x32_bf16 v[122:125], v[158:161], v[194:197], v[122:125]
	v_mfma_f32_16x16x32_bf16 v[122:125], v[154:157], v[190:193], v[122:125]
	v_mfma_f32_16x16x32_bf16 v[114:117], v[162:165], v[190:193], v[114:117]
	v_mfma_f32_16x16x32_bf16 v[114:117], v[166:169], v[194:197], v[114:117]
	v_mfma_f32_16x16x32_bf16 v[98:101], v[166:169], v[202:205], v[98:101]
	v_mfma_f32_16x16x32_bf16 v[98:101], v[162:165], v[198:201], v[98:101]
	v_mfma_f32_16x16x32_bf16 v[82:85], v[162:165], v[206:209], v[82:85]
	v_mfma_f32_16x16x32_bf16 v[82:85], v[166:169], v[228:231], v[82:85]
	v_mfma_f32_16x16x32_bf16 v[70:73], v[166:169], v[236:239], v[70:73]
	v_mfma_f32_16x16x32_bf16 v[70:73], v[162:165], v[232:235], v[70:73]
	v_mfma_f32_16x16x32_bf16 v[66:69], v[170:173], v[232:235], v[66:69]
	v_mfma_f32_16x16x32_bf16 v[66:69], v[178:181], v[236:239], v[66:69]
	v_mfma_f32_16x16x32_bf16 v[74:77], v[178:181], v[228:231], v[74:77]
	v_mfma_f32_16x16x32_bf16 v[74:77], v[170:173], v[206:209], v[74:77]
	v_mfma_f32_16x16x32_bf16 v[90:93], v[170:173], v[198:201], v[90:93]
	v_mfma_f32_16x16x32_bf16 v[90:93], v[178:181], v[202:205], v[90:93]
	v_mfma_f32_16x16x32_bf16 v[106:109], v[178:181], v[194:197], v[106:109]
	v_mfma_f32_16x16x32_bf16 v[106:109], v[170:173], v[190:193], v[106:109]
	s_barrier
	s_add_i32 s24, s53, s38
	v_lshl_add_u64 v[140:141], v[140:141], 0, s[34:35]
	s_mov_b32 m0, s24
	s_nop 0
	global_load_lds_dwordx4 v[140:141], off
	ds_read_b128 v[190:193], v145 offset:49152
	ds_read_b128 v[194:197], v145 offset:50176
	s_add_i32 m0, s24, 0x2000
	s_add_u32 s22, s22, 0x100080
	v_lshl_add_u64 v[140:141], v[186:187], 0, s[34:35]
	s_addc_u32 s23, s23, 0
	s_add_i32 s24, s54, s38
	global_load_lds_dwordx4 v[140:141], off
	ds_read_b128 v[198:201], v145 offset:51200
	ds_read_b128 v[202:205], v145 offset:52224
	v_lshl_add_u64 v[140:141], s[22:23], 0, v[0:1]
	s_mov_b32 m0, s24
	s_nop 0
	global_load_lds_dwordx4 v[140:141], off
	ds_read_b128 v[206:209], v145 offset:53248
	ds_read_b128 v[228:231], v145 offset:54272
	v_lshl_add_u64 v[140:141], s[22:23], 0, v[130:131]
	s_add_i32 m0, s24, 0x2000
	s_nop 0
	global_load_lds_dwordx4 v[140:141], off
	ds_read_b128 v[232:235], v145 offset:55296
	ds_read_b128 v[236:239], v145 offset:56320
	v_lshl_add_u64 v[140:141], v[188:189], 0, s[34:35]
	s_mov_b32 m0, s43
	s_nop 0
	global_load_lds_dwordx4 v[140:141], off
	s_add_i32 s52, s52, 2
	s_add_u32 s18, s18, 0x100
	s_addc_u32 s19, s19, 0
	s_add_u32 s50, s50, 0x100
	s_addc_u32 s51, s51, 0
	s_add_u32 s22, s18, 0xfff00080
	s_addc_u32 s23, s19, -1
	s_cmp_eq_u32 s52, 60
	s_cselect_b32 s25, s9, s23
	s_cselect_b32 s24, s48, s22
	s_cselect_b32 s23, s7, s51
	s_cselect_b32 s22, s49, s50
	v_lshl_add_u64 v[140:141], v[210:211], 0, s[34:35]
	s_mov_b32 m0, s44
	s_nop 0
	global_load_lds_dwordx4 v[140:141], off
	s_waitcnt vmcnt(8)
	s_waitcnt lgkmcnt(0)
	s_barrier
	v_mfma_f32_16x16x32_bf16 v[62:65], v[146:149], v[190:193], v[62:65]
	v_mfma_f32_16x16x32_bf16 v[62:65], v[150:153], v[194:197], v[62:65]
	v_mfma_f32_16x16x32_bf16 v[54:57], v[150:153], v[202:205], v[54:57]
	v_mfma_f32_16x16x32_bf16 v[54:57], v[146:149], v[198:201], v[54:57]
	v_mfma_f32_16x16x32_bf16 v[38:41], v[146:149], v[206:209], v[38:41]
	v_mfma_f32_16x16x32_bf16 v[38:41], v[150:153], v[228:231], v[38:41]
	v_mfma_f32_16x16x32_bf16 v[22:25], v[150:153], v[236:239], v[22:25]
	v_mfma_f32_16x16x32_bf16 v[22:25], v[146:149], v[232:235], v[22:25]
	v_mfma_f32_16x16x32_bf16 v[14:17], v[154:157], v[232:235], v[14:17]
	v_mfma_f32_16x16x32_bf16 v[14:17], v[158:161], v[236:239], v[14:17]
	v_mfma_f32_16x16x32_bf16 v[30:33], v[158:161], v[228:231], v[30:33]
	v_mfma_f32_16x16x32_bf16 v[30:33], v[154:157], v[206:209], v[30:33]
	v_mfma_f32_16x16x32_bf16 v[46:49], v[154:157], v[198:201], v[46:49]
	v_mfma_f32_16x16x32_bf16 v[46:49], v[158:161], v[202:205], v[46:49]
	v_mfma_f32_16x16x32_bf16 v[58:61], v[158:161], v[194:197], v[58:61]
	v_mfma_f32_16x16x32_bf16 v[58:61], v[154:157], v[190:193], v[58:61]
	v_mfma_f32_16x16x32_bf16 v[50:53], v[162:165], v[190:193], v[50:53]
	v_mfma_f32_16x16x32_bf16 v[50:53], v[166:169], v[194:197], v[50:53]
	v_mfma_f32_16x16x32_bf16 v[34:37], v[166:169], v[202:205], v[34:37]
	v_mfma_f32_16x16x32_bf16 v[34:37], v[162:165], v[198:201], v[34:37]
	v_mfma_f32_16x16x32_bf16 v[18:21], v[162:165], v[206:209], v[18:21]
	v_mfma_f32_16x16x32_bf16 v[18:21], v[166:169], v[228:231], v[18:21]
	v_mfma_f32_16x16x32_bf16 v[6:9], v[166:169], v[236:239], v[6:9]
	v_mfma_f32_16x16x32_bf16 v[6:9], v[162:165], v[232:235], v[6:9]
	v_mfma_f32_16x16x32_bf16 v[2:5], v[170:173], v[232:235], v[2:5]
	v_mfma_f32_16x16x32_bf16 v[2:5], v[178:181], v[236:239], v[2:5]
	v_mfma_f32_16x16x32_bf16 v[10:13], v[178:181], v[228:231], v[10:13]
	v_mfma_f32_16x16x32_bf16 v[10:13], v[170:173], v[206:209], v[10:13]
	v_mfma_f32_16x16x32_bf16 v[26:29], v[170:173], v[198:201], v[26:29]
	v_mfma_f32_16x16x32_bf16 v[26:29], v[178:181], v[202:205], v[26:29]
	v_mfma_f32_16x16x32_bf16 v[42:45], v[178:181], v[194:197], v[42:45]
	v_mfma_f32_16x16x32_bf16 v[42:45], v[170:173], v[190:193], v[42:45]
	s_barrier
	s_cmp_gt_u32 s52, 61
	s_cbranch_scc0 .LBB0_575
	s_and_b64 vcc, exec, s[4:5]
	s_cbranch_vccz .LBB0_578
	s_barrier

.Lz0_1_0:
	s_waitcnt vmcnt(8)
	s_waitcnt lgkmcnt(0)
	s_barrier
	v_mfma_f32_16x16x32_bf16 v[126:129], v[146:149], v[190:193], 0
	v_mfma_f32_16x16x32_bf16 v[126:129], v[150:153], v[194:197], v[126:129]
	v_mfma_f32_16x16x32_bf16 v[118:121], v[150:153], v[202:205], 0
	v_mfma_f32_16x16x32_bf16 v[118:121], v[146:149], v[198:201], v[118:121]
	v_mfma_f32_16x16x32_bf16 v[102:105], v[146:149], v[206:209], 0
	v_mfma_f32_16x16x32_bf16 v[102:105], v[150:153], v[228:231], v[102:105]
	v_mfma_f32_16x16x32_bf16 v[86:89], v[150:153], v[236:239], 0
	v_mfma_f32_16x16x32_bf16 v[86:89], v[146:149], v[232:235], v[86:89]
	v_mfma_f32_16x16x32_bf16 v[78:81], v[154:157], v[232:235], 0
	v_mfma_f32_16x16x32_bf16 v[78:81], v[158:161], v[236:239], v[78:81]
	v_mfma_f32_16x16x32_bf16 v[94:97], v[158:161], v[228:231], 0
	v_mfma_f32_16x16x32_bf16 v[94:97], v[154:157], v[206:209], v[94:97]
	v_mfma_f32_16x16x32_bf16 v[110:113], v[154:157], v[198:201], 0
	v_mfma_f32_16x16x32_bf16 v[110:113], v[158:161], v[202:205], v[110:113]
	v_mfma_f32_16x16x32_bf16 v[122:125], v[158:161], v[194:197], 0
	v_mfma_f32_16x16x32_bf16 v[122:125], v[154:157], v[190:193], v[122:125]
	v_mfma_f32_16x16x32_bf16 v[114:117], v[162:165], v[190:193], 0
	v_mfma_f32_16x16x32_bf16 v[114:117], v[166:169], v[194:197], v[114:117]
	v_mfma_f32_16x16x32_bf16 v[98:101], v[166:169], v[202:205], 0
	v_mfma_f32_16x16x32_bf16 v[98:101], v[162:165], v[198:201], v[98:101]
	v_mfma_f32_16x16x32_bf16 v[82:85], v[162:165], v[206:209], 0
	v_mfma_f32_16x16x32_bf16 v[82:85], v[166:169], v[228:231], v[82:85]
	v_mfma_f32_16x16x32_bf16 v[70:73], v[166:169], v[236:239], 0
	v_mfma_f32_16x16x32_bf16 v[70:73], v[162:165], v[232:235], v[70:73]
	v_mfma_f32_16x16x32_bf16 v[66:69], v[170:173], v[232:235], 0
	v_mfma_f32_16x16x32_bf16 v[66:69], v[178:181], v[236:239], v[66:69]
	v_mfma_f32_16x16x32_bf16 v[74:77], v[178:181], v[228:231], 0
	v_mfma_f32_16x16x32_bf16 v[74:77], v[170:173], v[206:209], v[74:77]
	v_mfma_f32_16x16x32_bf16 v[90:93], v[170:173], v[198:201], 0
	v_mfma_f32_16x16x32_bf16 v[90:93], v[178:181], v[202:205], v[90:93]
	v_mfma_f32_16x16x32_bf16 v[106:109], v[178:181], v[194:197], 0
	v_mfma_f32_16x16x32_bf16 v[106:109], v[170:173], v[190:193], v[106:109]
	s_barrier
	s_branch .Lz0_1_0_ret
.Lz0_1_1:
	s_waitcnt vmcnt(8)
	s_waitcnt lgkmcnt(0)
	s_barrier
	v_mfma_f32_16x16x32_bf16 v[62:65], v[146:149], v[190:193], 0
	v_mfma_f32_16x16x32_bf16 v[62:65], v[150:153], v[194:197], v[62:65]
	v_mfma_f32_16x16x32_bf16 v[54:57], v[150:153], v[202:205], 0
	v_mfma_f32_16x16x32_bf16 v[54:57], v[146:149], v[198:201], v[54:57]
	v_mfma_f32_16x16x32_bf16 v[38:41], v[146:149], v[206:209], 0
	v_mfma_f32_16x16x32_bf16 v[38:41], v[150:153], v[228:231], v[38:41]
	v_mfma_f32_16x16x32_bf16 v[22:25], v[150:153], v[236:239], 0
	v_mfma_f32_16x16x32_bf16 v[22:25], v[146:149], v[232:235], v[22:25]
	v_mfma_f32_16x16x32_bf16 v[14:17], v[154:157], v[232:235], 0
	v_mfma_f32_16x16x32_bf16 v[14:17], v[158:161], v[236:239], v[14:17]
	v_mfma_f32_16x16x32_bf16 v[30:33], v[158:161], v[228:231], 0
	v_mfma_f32_16x16x32_bf16 v[30:33], v[154:157], v[206:209], v[30:33]
	v_mfma_f32_16x16x32_bf16 v[46:49], v[154:157], v[198:201], 0
	v_mfma_f32_16x16x32_bf16 v[46:49], v[158:161], v[202:205], v[46:49]
	v_mfma_f32_16x16x32_bf16 v[58:61], v[158:161], v[194:197], 0
	v_mfma_f32_16x16x32_bf16 v[58:61], v[154:157], v[190:193], v[58:61]
	v_mfma_f32_16x16x32_bf16 v[50:53], v[162:165], v[190:193], 0
	v_mfma_f32_16x16x32_bf16 v[50:53], v[166:169], v[194:197], v[50:53]
	v_mfma_f32_16x16x32_bf16 v[34:37], v[166:169], v[202:205], 0
	v_mfma_f32_16x16x32_bf16 v[34:37], v[162:165], v[198:201], v[34:37]
	v_mfma_f32_16x16x32_bf16 v[18:21], v[162:165], v[206:209], 0
	v_mfma_f32_16x16x32_bf16 v[18:21], v[166:169], v[228:231], v[18:21]
	v_mfma_f32_16x16x32_bf16 v[6:9], v[166:169], v[236:239], 0
	v_mfma_f32_16x16x32_bf16 v[6:9], v[162:165], v[232:235], v[6:9]
	v_mfma_f32_16x16x32_bf16 v[2:5], v[170:173], v[232:235], 0
	v_mfma_f32_16x16x32_bf16 v[2:5], v[178:181], v[236:239], v[2:5]
	v_mfma_f32_16x16x32_bf16 v[10:13], v[178:181], v[228:231], 0
	v_mfma_f32_16x16x32_bf16 v[10:13], v[170:173], v[206:209], v[10:13]
	v_mfma_f32_16x16x32_bf16 v[26:29], v[170:173], v[198:201], 0
	v_mfma_f32_16x16x32_bf16 v[26:29], v[178:181], v[202:205], v[26:29]
	v_mfma_f32_16x16x32_bf16 v[42:45], v[178:181], v[194:197], 0
	v_mfma_f32_16x16x32_bf16 v[42:45], v[170:173], v[190:193], v[42:45]
	s_barrier
	s_branch .Lz0_1_1_ret

.LBB0_711:
	s_andn2_b64 vcc, exec, s[0:1]
	s_cbranch_vccnz .LBB0_785
	v_readlane_b32 s0, v253, 25
	v_readlane_b32 s1, v253, 26
	v_readlane_b32 s2, v251, 21
	s_andn2_b64 vcc, exec, s[0:1]
	s_waitcnt vmcnt(0)
	v_mbcnt_lo_u32_b32 v2, -1, 0
	v_mbcnt_hi_u32_b32 v2, -1, v2
	s_cbranch_vccnz .LBB0_728
	v_readlane_b32 s0, v255, 31
	s_add_u32 s24, s0, 0x7200000
	v_readlane_b32 s0, v255, 32
	s_addc_u32 s25, s0, 0
	s_lshl_b32 s26, s2, 10
	v_lshl_add_u32 v0, v2, 4, s26
	v_add_u32_e32 v4, 0x2000, v0
	v_ashrrev_i32_e32 v3, 31, v4
	v_lshrrev_b32_e32 v3, 22, v3
	v_add_u32_e32 v3, v4, v3
	v_ashrrev_i32_e32 v3, 10, v3
	v_mul_i32_i24_e32 v5, 0x400, v3
	v_sub_u32_e32 v4, v4, v5
	v_lshrrev_b32_e32 v5, 4, v4
	v_bitop3_b32 v5, v5, v4, 32 bitop3:0x6c
	v_ashrrev_i32_e32 v4, 31, v5
	v_lshrrev_b32_e32 v4, 26, v4
	v_add_u32_e32 v6, v5, v4
	v_ashrrev_i32_e32 v4, 6, v6
	v_lshlrev_b32_e32 v7, 3, v3
	v_and_b32_e32 v6, 0xffc0, v6
	v_and_b32_e32 v7, -16, v7
	v_sub_u32_e32 v5, v5, v6
	v_add_u32_e32 v7, v4, v7
	v_lshrrev_b16_e32 v6, 7, v5
	v_and_b32_e32 v8, 3, v4
	s_mov_b32 s0, 0x7ffe0
	v_lshrrev_b32_e32 v9, 2, v7
	v_lshlrev_b32_e32 v10, 1, v7
	v_and_b32_e32 v6, 1, v6
	v_and_or_b32 v8, v7, s0, v8
	v_and_b32_e32 v9, 4, v9
	v_and_b32_e32 v10, 24, v10
	v_add_u16_e32 v5, v5, v6
	v_or3_b32 v8, v8, v9, v10
	v_lshlrev_b32_e32 v9, 5, v3
	v_ashrrev_i16_sdwa v5, v212, sext(v5) dst_sel:DWORD dst_unused:UNUSED_PAD src0_sel:DWORD src1_sel:BYTE_0
	v_and_b32_e32 v9, 32, v9
	v_bfe_i32 v5, v5, 0, 16
	v_add_lshl_u32 v6, v9, v5, 1
	v_lshl_add_u32 v130, v8, 13, v6
	v_lshl_add_u32 v132, v7, 13, v6
	v_ashrrev_i32_e32 v6, 31, v0
	v_lshrrev_b32_e32 v6, 22, v6
	v_add_u32_e32 v6, v0, v6
	v_ashrrev_i32_e32 v6, 10, v6
	v_mul_i32_i24_e32 v7, 0x400, v6
	v_sub_u32_e32 v0, v0, v7
	v_lshrrev_b32_e32 v7, 4, v0
	v_bitop3_b32 v0, v7, v0, 32 bitop3:0x6c
	v_ashrrev_i32_e32 v7, 31, v0
	v_lshrrev_b32_e32 v7, 26, v7
	v_add_u32_e32 v8, v0, v7
	v_lshlrev_b32_e32 v9, 3, v6
	v_ashrrev_i32_e32 v7, 6, v8
	v_and_b32_e32 v9, -16, v9
	v_add_u32_e32 v9, v7, v9
	v_and_b32_e32 v10, 3, v7
	v_lshrrev_b32_e32 v11, 2, v9
	v_lshlrev_b32_e32 v12, 1, v9
	v_and_b32_e32 v8, 0xc0, v8
	v_and_or_b32 v10, v9, s0, v10
	v_and_b32_e32 v11, 4, v11
	v_and_b32_e32 v12, 24, v12
	v_sub_u32_e32 v0, v0, v8
	s_ashr_i32 s3, s2, 2
	v_or3_b32 v10, v10, v11, v12
	v_lshlrev_b32_e32 v11, 5, v6
	v_ashrrev_i16_sdwa v0, v212, sext(v0) dst_sel:DWORD dst_unused:UNUSED_PAD src0_sel:DWORD src1_sel:BYTE_0
	v_readlane_b32 s0, v254, 22
	v_and_b32_e32 v11, 32, v11
	v_bfe_i32 v8, v0, 0, 16
	v_readlane_b32 s1, v254, 23
	s_add_u32 s18, s24, s0
	v_add_lshl_u32 v11, v11, v8, 1
	s_addc_u32 s19, s25, s1
	s_add_i32 s31, s26, 0
	v_lshl_add_u32 v0, v10, 13, v11
	s_add_i32 m0, s31, 0x10000
	v_lshl_add_u32 v134, v9, 13, v11
	global_load_lds_dwordx4 v0, s[18:19]
	s_add_i32 m0, s31, 0x12000
	s_add_u32 s0, s18, 0x100000
	global_load_lds_dwordx4 v130, s[18:19]
	s_addc_u32 s1, s19, 0
	s_add_i32 m0, s31, 0x14000
	s_add_i32 s40, s31, 0x2000
	global_load_lds_dwordx4 v0, s[0:1]
	s_add_i32 m0, s31, 0x16000
	s_add_i32 s41, s31, 0x4000
	global_load_lds_dwordx4 v130, s[0:1]
	v_readlane_b32 s0, v254, 26
	s_mov_b32 m0, s31
	v_readlane_b32 s1, v254, 27
	s_add_i32 s42, s31, 0x6000
	s_cmp_eq_u32 s3, 1
	s_nop 2
	global_load_lds_dwordx4 v134, s[0:1]
	s_mov_b32 m0, s40
	s_nop 0
	global_load_lds_dwordx4 v132, s[0:1]
	v_readlane_b32 s0, v254, 28
	s_mov_b32 m0, s41
	v_readlane_b32 s1, v254, 29
	s_nop 4
	global_load_lds_dwordx4 v134, s[0:1]
	s_mov_b32 m0, s42
	s_nop 0
	global_load_lds_dwordx4 v132, s[0:1]
	s_cselect_b64 s[0:1], -1, 0
	s_cmp_lg_u32 s3, 1
	s_cbranch_scc1 .LBB0_715
	s_barrier
	s_setprio 1

.LBB0_721:
	s_add_i32 s53, 0, 0x10000
	v_add_u32_e32 v140, s53, v143
	s_add_i32 s56, 0, 0x14000
	ds_read_b128 v[146:149], v140
	ds_read_b128 v[150:153], v140 offset:1024
	ds_read_b128 v[154:157], v140 offset:2048
	ds_read_b128 v[158:161], v140 offset:3072
	v_add_u32_e32 v140, s56, v143
	ds_read_b128 v[162:165], v140
	ds_read_b128 v[166:169], v140 offset:1024
	ds_read_b128 v[170:173], v140 offset:2048
	ds_read_b128 v[178:181], v140 offset:3072
	v_lshl_add_u64 v[140:141], s[16:17], 0, v[136:137]
	s_add_i32 m0, s31, 0xc000
	ds_read_b128 v[190:193], v145
	ds_read_b128 v[194:197], v145 offset:1024
	ds_read_b128 v[198:201], v145 offset:2048
	ds_read_b128 v[202:205], v145 offset:3072
	ds_read_b128 v[206:209], v145 offset:4096
	ds_read_b128 v[228:231], v145 offset:5120
	ds_read_b128 v[232:235], v145 offset:6144
	ds_read_b128 v[236:239], v145 offset:7168
	global_load_lds_dwordx4 v[140:141], off
	v_lshl_add_u64 v[140:141], s[16:17], 0, v[138:139]
	s_add_i32 m0, s31, 0xe000
	s_nop 0
	global_load_lds_dwordx4 v[140:141], off
	s_cmp_eq_u32 s52, -2
	s_cbranch_scc1 .Lz0_2_0
	s_waitcnt vmcnt(8)
	s_waitcnt lgkmcnt(0)
	s_barrier
	v_mfma_f32_16x16x32_bf16 v[126:129], v[146:149], v[190:193], v[126:129]
	v_mfma_f32_16x16x32_bf16 v[126:129], v[150:153], v[194:197], v[126:129]
	v_mfma_f32_16x16x32_bf16 v[110:113], v[150:153], v[202:205], v[110:113]
	v_mfma_f32_16x16x32_bf16 v[110:113], v[146:149], v[198:201], v[110:113]
	v_mfma_f32_16x16x32_bf16 v[94:97], v[146:149], v[206:209], v[94:97]
	v_mfma_f32_16x16x32_bf16 v[94:97], v[150:153], v[228:231], v[94:97]
	v_mfma_f32_16x16x32_bf16 v[78:81], v[150:153], v[236:239], v[78:81]
	v_mfma_f32_16x16x32_bf16 v[78:81], v[146:149], v[232:235], v[78:81]
	v_mfma_f32_16x16x32_bf16 v[70:73], v[154:157], v[232:235], v[70:73]
	v_mfma_f32_16x16x32_bf16 v[70:73], v[158:161], v[236:239], v[70:73]
	v_mfma_f32_16x16x32_bf16 v[86:89], v[158:161], v[228:231], v[86:89]
	v_mfma_f32_16x16x32_bf16 v[86:89], v[154:157], v[206:209], v[86:89]
	v_mfma_f32_16x16x32_bf16 v[102:105], v[154:157], v[198:201], v[102:105]
	v_mfma_f32_16x16x32_bf16 v[102:105], v[158:161], v[202:205], v[102:105]
	v_mfma_f32_16x16x32_bf16 v[118:121], v[158:161], v[194:197], v[118:121]
	v_mfma_f32_16x16x32_bf16 v[118:121], v[154:157], v[190:193], v[118:121]
	v_mfma_f32_16x16x32_bf16 v[122:125], v[162:165], v[190:193], v[122:125]
	v_mfma_f32_16x16x32_bf16 v[122:125], v[166:169], v[194:197], v[122:125]
	v_mfma_f32_16x16x32_bf16 v[106:109], v[166:169], v[202:205], v[106:109]
	v_mfma_f32_16x16x32_bf16 v[106:109], v[162:165], v[198:201], v[106:109]
	v_mfma_f32_16x16x32_bf16 v[90:93], v[162:165], v[206:209], v[90:93]
	v_mfma_f32_16x16x32_bf16 v[90:93], v[166:169], v[228:231], v[90:93]
	v_mfma_f32_16x16x32_bf16 v[74:77], v[166:169], v[236:239], v[74:77]
	v_mfma_f32_16x16x32_bf16 v[74:77], v[162:165], v[232:235], v[74:77]
	v_mfma_f32_16x16x32_bf16 v[66:69], v[170:173], v[232:235], v[66:69]
	v_mfma_f32_16x16x32_bf16 v[66:69], v[178:181], v[236:239], v[66:69]
	v_mfma_f32_16x16x32_bf16 v[82:85], v[178:181], v[228:231], v[82:85]
	v_mfma_f32_16x16x32_bf16 v[82:85], v[170:173], v[206:209], v[82:85]
	v_mfma_f32_16x16x32_bf16 v[98:101], v[170:173], v[198:201], v[98:101]
	v_mfma_f32_16x16x32_bf16 v[98:101], v[178:181], v[202:205], v[98:101]
	v_mfma_f32_16x16x32_bf16 v[114:117], v[178:181], v[194:197], v[114:117]
	v_mfma_f32_16x16x32_bf16 v[114:117], v[170:173], v[190:193], v[114:117]
	s_barrier
.Lz0_2_0_ret:
	s_add_i32 s53, s53, s26
	v_lshl_add_u64 v[140:141], s[18:19], 0, v[0:1]
	s_mov_b32 m0, s53
	s_nop 0
	global_load_lds_dwordx4 v[140:141], off
	ds_read_b128 v[190:193], v145 offset:16384
	ds_read_b128 v[194:197], v145 offset:17408
	s_add_i32 m0, s53, 0x2000
	s_add_u32 s54, s18, 0x100000
	v_lshl_add_u64 v[186:187], s[18:19], 0, v[130:131]
	s_addc_u32 s55, s19, 0
	s_add_i32 s53, s56, s26
	global_load_lds_dwordx4 v[186:187], off
	ds_read_b128 v[198:201], v145 offset:18432
	ds_read_b128 v[202:205], v145 offset:19456
	v_lshl_add_u64 v[188:189], s[54:55], 0, v[0:1]
	s_mov_b32 m0, s53
	v_lshl_add_u64 v[210:211], s[22:23], 0, v[132:133]
	global_load_lds_dwordx4 v[188:189], off
	ds_read_b128 v[206:209], v145 offset:20480
	ds_read_b128 v[228:231], v145 offset:21504
	v_lshl_add_u64 v[188:189], s[54:55], 0, v[130:131]
	s_add_i32 m0, s53, 0x2000
	s_nop 0
	global_load_lds_dwordx4 v[188:189], off
	ds_read_b128 v[232:235], v145 offset:22528
	ds_read_b128 v[236:239], v145 offset:23552
	v_lshl_add_u64 v[188:189], s[22:23], 0, v[134:135]
	s_mov_b32 m0, s31
	s_nop 0
	global_load_lds_dwordx4 v[188:189], off
	s_mov_b32 m0, s40
	s_nop 0
	global_load_lds_dwordx4 v[210:211], off
	s_cmp_eq_u32 s52, -2
	s_cbranch_scc1 .Lz0_2_1
	s_waitcnt vmcnt(8)
	s_waitcnt lgkmcnt(0)
	s_barrier
	v_mfma_f32_16x16x32_bf16 v[62:65], v[146:149], v[190:193], v[62:65]
	v_mfma_f32_16x16x32_bf16 v[62:65], v[150:153], v[194:197], v[62:65]
	v_mfma_f32_16x16x32_bf16 v[46:49], v[150:153], v[202:205], v[46:49]
	v_mfma_f32_16x16x32_bf16 v[46:49], v[146:149], v[198:201], v[46:49]
	v_mfma_f32_16x16x32_bf16 v[30:33], v[146:149], v[206:209], v[30:33]
	v_mfma_f32_16x16x32_bf16 v[30:33], v[150:153], v[228:231], v[30:33]
	v_mfma_f32_16x16x32_bf16 v[14:17], v[150:153], v[236:239], v[14:17]
	v_mfma_f32_16x16x32_bf16 v[14:17], v[146:149], v[232:235], v[14:17]
	v_mfma_f32_16x16x32_bf16 v[6:9], v[154:157], v[232:235], v[6:9]
	v_mfma_f32_16x16x32_bf16 v[6:9], v[158:161], v[236:239], v[6:9]
	v_mfma_f32_16x16x32_bf16 v[22:25], v[158:161], v[228:231], v[22:25]
	v_mfma_f32_16x16x32_bf16 v[22:25], v[154:157], v[206:209], v[22:25]
	v_mfma_f32_16x16x32_bf16 v[38:41], v[154:157], v[198:201], v[38:41]
	v_mfma_f32_16x16x32_bf16 v[38:41], v[158:161], v[202:205], v[38:41]
	v_mfma_f32_16x16x32_bf16 v[54:57], v[158:161], v[194:197], v[54:57]
	v_mfma_f32_16x16x32_bf16 v[54:57], v[154:157], v[190:193], v[54:57]
	v_mfma_f32_16x16x32_bf16 v[58:61], v[162:165], v[190:193], v[58:61]
	v_mfma_f32_16x16x32_bf16 v[58:61], v[166:169], v[194:197], v[58:61]
	v_mfma_f32_16x16x32_bf16 v[42:45], v[166:169], v[202:205], v[42:45]
	v_mfma_f32_16x16x32_bf16 v[42:45], v[162:165], v[198:201], v[42:45]
	v_mfma_f32_16x16x32_bf16 v[26:29], v[162:165], v[206:209], v[26:29]
	v_mfma_f32_16x16x32_bf16 v[26:29], v[166:169], v[228:231], v[26:29]
	v_mfma_f32_16x16x32_bf16 v[10:13], v[166:169], v[236:239], v[10:13]
	v_mfma_f32_16x16x32_bf16 v[10:13], v[162:165], v[232:235], v[10:13]
	v_mfma_f32_16x16x32_bf16 v[2:5], v[170:173], v[232:235], v[2:5]
	v_mfma_f32_16x16x32_bf16 v[2:5], v[178:181], v[236:239], v[2:5]
	v_mfma_f32_16x16x32_bf16 v[18:21], v[178:181], v[228:231], v[18:21]
	v_mfma_f32_16x16x32_bf16 v[18:21], v[170:173], v[206:209], v[18:21]
	v_mfma_f32_16x16x32_bf16 v[34:37], v[170:173], v[198:201], v[34:37]
	v_mfma_f32_16x16x32_bf16 v[34:37], v[178:181], v[202:205], v[34:37]
	v_mfma_f32_16x16x32_bf16 v[50:53], v[178:181], v[194:197], v[50:53]
	v_mfma_f32_16x16x32_bf16 v[50:53], v[170:173], v[190:193], v[50:53]
	s_barrier
.Lz0_2_1_ret:
	s_add_i32 s53, 0, 0x18000
	s_add_i32 s54, 0, 0x1c000
	v_add_u32_e32 v158, s53, v143
	v_add_u32_e32 v175, s54, v143
	ds_read_b128 v[146:149], v158
	ds_read_b128 v[150:153], v158 offset:1024
	ds_read_b128 v[154:157], v158 offset:2048
	ds_read_b128 v[158:161], v158 offset:3072
	ds_read_b128 v[162:165], v175
	ds_read_b128 v[166:169], v175 offset:1024
	ds_read_b128 v[170:173], v175 offset:2048
	ds_read_b128 v[178:181], v175 offset:3072
	s_add_u32 s22, s22, 0x100000
	s_addc_u32 s23, s23, 0
	s_mov_b32 m0, s41
	v_lshl_add_u64 v[226:227], s[22:23], 0, v[134:135]
	ds_read_b128 v[190:193], v145 offset:32768
	ds_read_b128 v[194:197], v145 offset:33792
	ds_read_b128 v[198:201], v145 offset:34816
	ds_read_b128 v[202:205], v145 offset:35840
	ds_read_b128 v[206:209], v145 offset:36864
	ds_read_b128 v[228:231], v145 offset:37888
	ds_read_b128 v[232:235], v145 offset:38912
	ds_read_b128 v[236:239], v145 offset:39936
	global_load_lds_dwordx4 v[226:227], off
	v_lshl_add_u64 v[226:227], s[22:23], 0, v[132:133]
	s_mov_b32 m0, s42
	s_nop 0
	global_load_lds_dwordx4 v[226:227], off
	s_waitcnt vmcnt(8)
	s_waitcnt lgkmcnt(0)
	s_barrier
	v_mfma_f32_16x16x32_bf16 v[126:129], v[146:149], v[190:193], v[126:129]
	v_mfma_f32_16x16x32_bf16 v[126:129], v[150:153], v[194:197], v[126:129]
	v_mfma_f32_16x16x32_bf16 v[110:113], v[150:153], v[202:205], v[110:113]
	v_mfma_f32_16x16x32_bf16 v[110:113], v[146:149], v[198:201], v[110:113]
	v_mfma_f32_16x16x32_bf16 v[94:97], v[146:149], v[206:209], v[94:97]
	v_mfma_f32_16x16x32_bf16 v[94:97], v[150:153], v[228:231], v[94:97]
	v_mfma_f32_16x16x32_bf16 v[78:81], v[150:153], v[236:239], v[78:81]
	v_mfma_f32_16x16x32_bf16 v[78:81], v[146:149], v[232:235], v[78:81]
	v_mfma_f32_16x16x32_bf16 v[70:73], v[154:157], v[232:235], v[70:73]
	v_mfma_f32_16x16x32_bf16 v[70:73], v[158:161], v[236:239], v[70:73]
	v_mfma_f32_16x16x32_bf16 v[86:89], v[158:161], v[228:231], v[86:89]
	v_mfma_f32_16x16x32_bf16 v[86:89], v[154:157], v[206:209], v[86:89]
	v_mfma_f32_16x16x32_bf16 v[102:105], v[154:157], v[198:201], v[102:105]
	v_mfma_f32_16x16x32_bf16 v[102:105], v[158:161], v[202:205], v[102:105]
	v_mfma_f32_16x16x32_bf16 v[118:121], v[158:161], v[194:197], v[118:121]
	v_mfma_f32_16x16x32_bf16 v[118:121], v[154:157], v[190:193], v[118:121]
	v_mfma_f32_16x16x32_bf16 v[122:125], v[162:165], v[190:193], v[122:125]
	v_mfma_f32_16x16x32_bf16 v[122:125], v[166:169], v[194:197], v[122:125]
	v_mfma_f32_16x16x32_bf16 v[106:109], v[166:169], v[202:205], v[106:109]
	v_mfma_f32_16x16x32_bf16 v[106:109], v[162:165], v[198:201], v[106:109]
	v_mfma_f32_16x16x32_bf16 v[90:93], v[162:165], v[206:209], v[90:93]
	v_mfma_f32_16x16x32_bf16 v[90:93], v[166:169], v[228:231], v[90:93]
	v_mfma_f32_16x16x32_bf16 v[74:77], v[166:169], v[236:239], v[74:77]
	v_mfma_f32_16x16x32_bf16 v[74:77], v[162:165], v[232:235], v[74:77]
	v_mfma_f32_16x16x32_bf16 v[66:69], v[170:173], v[232:235], v[66:69]
	v_mfma_f32_16x16x32_bf16 v[66:69], v[178:181], v[236:239], v[66:69]
	v_mfma_f32_16x16x32_bf16 v[82:85], v[178:181], v[228:231], v[82:85]
	v_mfma_f32_16x16x32_bf16 v[82:85], v[170:173], v[206:209], v[82:85]
	v_mfma_f32_16x16x32_bf16 v[98:101], v[170:173], v[198:201], v[98:101]
	v_mfma_f32_16x16x32_bf16 v[98:101], v[178:181], v[202:205], v[98:101]
	v_mfma_f32_16x16x32_bf16 v[114:117], v[178:181], v[194:197], v[114:117]
	v_mfma_f32_16x16x32_bf16 v[114:117], v[170:173], v[190:193], v[114:117]
	s_barrier
	s_add_i32 s22, s53, s26
	v_lshl_add_u64 v[140:141], v[140:141], 0, s[34:35]
	s_mov_b32 m0, s22
	s_nop 0
	global_load_lds_dwordx4 v[140:141], off
	ds_read_b128 v[190:193], v145 offset:49152
	ds_read_b128 v[194:197], v145 offset:50176
	s_add_i32 m0, s22, 0x2000
	s_add_u32 s18, s18, 0x100080
	v_lshl_add_u64 v[140:141], v[186:187], 0, s[34:35]
	s_addc_u32 s19, s19, 0
	s_add_i32 s22, s54, s26
	global_load_lds_dwordx4 v[140:141], off
	ds_read_b128 v[198:201], v145 offset:51200
	ds_read_b128 v[202:205], v145 offset:52224
	v_lshl_add_u64 v[140:141], s[18:19], 0, v[0:1]
	s_mov_b32 m0, s22
	s_nop 0
	global_load_lds_dwordx4 v[140:141], off
	ds_read_b128 v[206:209], v145 offset:53248
	ds_read_b128 v[228:231], v145 offset:54272
	v_lshl_add_u64 v[140:141], s[18:19], 0, v[130:131]
	s_add_i32 m0, s22, 0x2000
	s_nop 0
	global_load_lds_dwordx4 v[140:141], off
	ds_read_b128 v[232:235], v145 offset:55296
	ds_read_b128 v[236:239], v145 offset:56320
	v_lshl_add_u64 v[140:141], v[188:189], 0, s[34:35]
	s_mov_b32 m0, s43
	s_nop 0
	global_load_lds_dwordx4 v[140:141], off
	s_add_i32 s52, s52, 2
	s_add_u32 s16, s16, 0x100
	s_addc_u32 s17, s17, 0
	s_add_u32 s50, s50, 0x100
	s_addc_u32 s51, s51, 0
	s_add_u32 s18, s16, 0xfff00080
	s_addc_u32 s19, s17, -1
	s_cmp_eq_u32 s52, 60
	s_cselect_b32 s23, s7, s19
	s_cselect_b32 s22, s48, s18
	s_cselect_b32 s19, s5, s51
	s_cselect_b32 s18, s49, s50
	v_lshl_add_u64 v[140:141], v[210:211], 0, s[34:35]
	s_mov_b32 m0, s44
	s_nop 0
	global_load_lds_dwordx4 v[140:141], off
	s_waitcnt vmcnt(8)
	s_waitcnt lgkmcnt(0)
	s_barrier
	v_mfma_f32_16x16x32_bf16 v[62:65], v[146:149], v[190:193], v[62:65]
	v_mfma_f32_16x16x32_bf16 v[62:65], v[150:153], v[194:197], v[62:65]
	v_mfma_f32_16x16x32_bf16 v[46:49], v[150:153], v[202:205], v[46:49]
	v_mfma_f32_16x16x32_bf16 v[46:49], v[146:149], v[198:201], v[46:49]
	v_mfma_f32_16x16x32_bf16 v[30:33], v[146:149], v[206:209], v[30:33]
	v_mfma_f32_16x16x32_bf16 v[30:33], v[150:153], v[228:231], v[30:33]
	v_mfma_f32_16x16x32_bf16 v[14:17], v[150:153], v[236:239], v[14:17]
	v_mfma_f32_16x16x32_bf16 v[14:17], v[146:149], v[232:235], v[14:17]
	v_mfma_f32_16x16x32_bf16 v[6:9], v[154:157], v[232:235], v[6:9]
	v_mfma_f32_16x16x32_bf16 v[6:9], v[158:161], v[236:239], v[6:9]
	v_mfma_f32_16x16x32_bf16 v[22:25], v[158:161], v[228:231], v[22:25]
	v_mfma_f32_16x16x32_bf16 v[22:25], v[154:157], v[206:209], v[22:25]
	v_mfma_f32_16x16x32_bf16 v[38:41], v[154:157], v[198:201], v[38:41]
	v_mfma_f32_16x16x32_bf16 v[38:41], v[158:161], v[202:205], v[38:41]
	v_mfma_f32_16x16x32_bf16 v[54:57], v[158:161], v[194:197], v[54:57]
	v_mfma_f32_16x16x32_bf16 v[54:57], v[154:157], v[190:193], v[54:57]
	v_mfma_f32_16x16x32_bf16 v[58:61], v[162:165], v[190:193], v[58:61]
	v_mfma_f32_16x16x32_bf16 v[58:61], v[166:169], v[194:197], v[58:61]
	v_mfma_f32_16x16x32_bf16 v[42:45], v[166:169], v[202:205], v[42:45]
	v_mfma_f32_16x16x32_bf16 v[42:45], v[162:165], v[198:201], v[42:45]
	v_mfma_f32_16x16x32_bf16 v[26:29], v[162:165], v[206:209], v[26:29]
	v_mfma_f32_16x16x32_bf16 v[26:29], v[166:169], v[228:231], v[26:29]
	v_mfma_f32_16x16x32_bf16 v[10:13], v[166:169], v[236:239], v[10:13]
	v_mfma_f32_16x16x32_bf16 v[10:13], v[162:165], v[232:235], v[10:13]
	v_mfma_f32_16x16x32_bf16 v[2:5], v[170:173], v[232:235], v[2:5]
	v_mfma_f32_16x16x32_bf16 v[2:5], v[178:181], v[236:239], v[2:5]
	v_mfma_f32_16x16x32_bf16 v[18:21], v[178:181], v[228:231], v[18:21]
	v_mfma_f32_16x16x32_bf16 v[18:21], v[170:173], v[206:209], v[18:21]
	v_mfma_f32_16x16x32_bf16 v[34:37], v[170:173], v[198:201], v[34:37]
	v_mfma_f32_16x16x32_bf16 v[34:37], v[178:181], v[202:205], v[34:37]
	v_mfma_f32_16x16x32_bf16 v[50:53], v[178:181], v[194:197], v[50:53]
	v_mfma_f32_16x16x32_bf16 v[50:53], v[170:173], v[190:193], v[50:53]
	s_barrier
	s_cmp_gt_u32 s52, 61
	s_cbranch_scc0 .LBB0_721
	s_and_b64 vcc, exec, s[2:3]
	s_cbranch_vccz .LBB0_724
	s_barrier

.Lz0_2_0:
	s_waitcnt vmcnt(8)
	s_waitcnt lgkmcnt(0)
	s_barrier
	v_mfma_f32_16x16x32_bf16 v[126:129], v[146:149], v[190:193], 0
	v_mfma_f32_16x16x32_bf16 v[126:129], v[150:153], v[194:197], v[126:129]
	v_mfma_f32_16x16x32_bf16 v[110:113], v[150:153], v[202:205], 0
	v_mfma_f32_16x16x32_bf16 v[110:113], v[146:149], v[198:201], v[110:113]
	v_mfma_f32_16x16x32_bf16 v[94:97], v[146:149], v[206:209], 0
	v_mfma_f32_16x16x32_bf16 v[94:97], v[150:153], v[228:231], v[94:97]
	v_mfma_f32_16x16x32_bf16 v[78:81], v[150:153], v[236:239], 0
	v_mfma_f32_16x16x32_bf16 v[78:81], v[146:149], v[232:235], v[78:81]
	v_mfma_f32_16x16x32_bf16 v[70:73], v[154:157], v[232:235], 0
	v_mfma_f32_16x16x32_bf16 v[70:73], v[158:161], v[236:239], v[70:73]
	v_mfma_f32_16x16x32_bf16 v[86:89], v[158:161], v[228:231], 0
	v_mfma_f32_16x16x32_bf16 v[86:89], v[154:157], v[206:209], v[86:89]
	v_mfma_f32_16x16x32_bf16 v[102:105], v[154:157], v[198:201], 0
	v_mfma_f32_16x16x32_bf16 v[102:105], v[158:161], v[202:205], v[102:105]
	v_mfma_f32_16x16x32_bf16 v[118:121], v[158:161], v[194:197], 0
	v_mfma_f32_16x16x32_bf16 v[118:121], v[154:157], v[190:193], v[118:121]
	v_mfma_f32_16x16x32_bf16 v[122:125], v[162:165], v[190:193], 0
	v_mfma_f32_16x16x32_bf16 v[122:125], v[166:169], v[194:197], v[122:125]
	v_mfma_f32_16x16x32_bf16 v[106:109], v[166:169], v[202:205], 0
	v_mfma_f32_16x16x32_bf16 v[106:109], v[162:165], v[198:201], v[106:109]
	v_mfma_f32_16x16x32_bf16 v[90:93], v[162:165], v[206:209], 0
	v_mfma_f32_16x16x32_bf16 v[90:93], v[166:169], v[228:231], v[90:93]
	v_mfma_f32_16x16x32_bf16 v[74:77], v[166:169], v[236:239], 0
	v_mfma_f32_16x16x32_bf16 v[74:77], v[162:165], v[232:235], v[74:77]
	v_mfma_f32_16x16x32_bf16 v[66:69], v[170:173], v[232:235], 0
	v_mfma_f32_16x16x32_bf16 v[66:69], v[178:181], v[236:239], v[66:69]
	v_mfma_f32_16x16x32_bf16 v[82:85], v[178:181], v[228:231], 0
	v_mfma_f32_16x16x32_bf16 v[82:85], v[170:173], v[206:209], v[82:85]
	v_mfma_f32_16x16x32_bf16 v[98:101], v[170:173], v[198:201], 0
	v_mfma_f32_16x16x32_bf16 v[98:101], v[178:181], v[202:205], v[98:101]
	v_mfma_f32_16x16x32_bf16 v[114:117], v[178:181], v[194:197], 0
	v_mfma_f32_16x16x32_bf16 v[114:117], v[170:173], v[190:193], v[114:117]
	s_barrier
	s_branch .Lz0_2_0_ret
.Lz0_2_1:
	s_waitcnt vmcnt(8)
	s_waitcnt lgkmcnt(0)
	s_barrier
	v_mfma_f32_16x16x32_bf16 v[62:65], v[146:149], v[190:193], 0
	v_mfma_f32_16x16x32_bf16 v[62:65], v[150:153], v[194:197], v[62:65]
	v_mfma_f32_16x16x32_bf16 v[46:49], v[150:153], v[202:205], 0
	v_mfma_f32_16x16x32_bf16 v[46:49], v[146:149], v[198:201], v[46:49]
	v_mfma_f32_16x16x32_bf16 v[30:33], v[146:149], v[206:209], 0
	v_mfma_f32_16x16x32_bf16 v[30:33], v[150:153], v[228:231], v[30:33]
	v_mfma_f32_16x16x32_bf16 v[14:17], v[150:153], v[236:239], 0
	v_mfma_f32_16x16x32_bf16 v[14:17], v[146:149], v[232:235], v[14:17]
	v_mfma_f32_16x16x32_bf16 v[6:9], v[154:157], v[232:235], 0
	v_mfma_f32_16x16x32_bf16 v[6:9], v[158:161], v[236:239], v[6:9]
	v_mfma_f32_16x16x32_bf16 v[22:25], v[158:161], v[228:231], 0
	v_mfma_f32_16x16x32_bf16 v[22:25], v[154:157], v[206:209], v[22:25]
	v_mfma_f32_16x16x32_bf16 v[38:41], v[154:157], v[198:201], 0
	v_mfma_f32_16x16x32_bf16 v[38:41], v[158:161], v[202:205], v[38:41]
	v_mfma_f32_16x16x32_bf16 v[54:57], v[158:161], v[194:197], 0
	v_mfma_f32_16x16x32_bf16 v[54:57], v[154:157], v[190:193], v[54:57]
	v_mfma_f32_16x16x32_bf16 v[58:61], v[162:165], v[190:193], 0
	v_mfma_f32_16x16x32_bf16 v[58:61], v[166:169], v[194:197], v[58:61]
	v_mfma_f32_16x16x32_bf16 v[42:45], v[166:169], v[202:205], 0
	v_mfma_f32_16x16x32_bf16 v[42:45], v[162:165], v[198:201], v[42:45]
	v_mfma_f32_16x16x32_bf16 v[26:29], v[162:165], v[206:209], 0
	v_mfma_f32_16x16x32_bf16 v[26:29], v[166:169], v[228:231], v[26:29]
	v_mfma_f32_16x16x32_bf16 v[10:13], v[166:169], v[236:239], 0
	v_mfma_f32_16x16x32_bf16 v[10:13], v[162:165], v[232:235], v[10:13]
	v_mfma_f32_16x16x32_bf16 v[2:5], v[170:173], v[232:235], 0
	v_mfma_f32_16x16x32_bf16 v[2:5], v[178:181], v[236:239], v[2:5]
	v_mfma_f32_16x16x32_bf16 v[18:21], v[178:181], v[228:231], 0
	v_mfma_f32_16x16x32_bf16 v[18:21], v[170:173], v[206:209], v[18:21]
	v_mfma_f32_16x16x32_bf16 v[34:37], v[170:173], v[198:201], 0
	v_mfma_f32_16x16x32_bf16 v[34:37], v[178:181], v[202:205], v[34:37]
	v_mfma_f32_16x16x32_bf16 v[50:53], v[178:181], v[194:197], 0
	v_mfma_f32_16x16x32_bf16 v[50:53], v[170:173], v[190:193], v[50:53]
	s_barrier
	s_branch .Lz0_2_1_ret

.LBB0_787:
	s_andn2_b64 vcc, exec, s[0:1]
	s_cbranch_vccnz .LBB0_864
	v_readlane_b32 s0, v251, 21
	s_and_b64 vcc, exec, s[36:37]
	s_waitcnt vmcnt(0)
	v_mbcnt_lo_u32_b32 v7, -1, 0
	v_mbcnt_hi_u32_b32 v7, -1, v7
	s_cbranch_vccnz .LBB0_812
	v_readlane_b32 s1, v255, 31
	s_add_u32 s24, s1, 0x11e00000
	v_readlane_b32 s1, v255, 32
	s_addc_u32 s25, s1, 0
	s_lshl_b32 s26, s0, 10
	v_lshl_add_u32 v0, v7, 4, s26
	v_add_u32_e32 v2, 0x2000, v0
	v_ashrrev_i32_e32 v3, 31, v2
	v_lshrrev_b32_e32 v3, 22, v3
	v_add_u32_e32 v3, v2, v3
	v_ashrrev_i32_e32 v6, 10, v3
	v_mul_i32_i24_e32 v3, 0x400, v6
	v_sub_u32_e32 v2, v2, v3
	v_lshrrev_b32_e32 v3, 4, v2
	v_bitop3_b32 v2, v3, v2, 32 bitop3:0x6c
	v_ashrrev_i32_e32 v3, 31, v2
	v_lshrrev_b32_e32 v3, 26, v3
	v_add_u32_e32 v3, v2, v3
	v_ashrrev_i32_e32 v8, 6, v3
	v_lshlrev_b32_e32 v4, 3, v6
	v_and_b32_e32 v3, 0xffc0, v3
	v_and_b32_e32 v4, -16, v4
	v_sub_u32_e32 v2, v2, v3
	v_add_u32_e32 v4, v8, v4
	v_lshrrev_b16_e32 v3, 7, v2
	v_and_b32_e32 v5, 3, v8
	s_mov_b32 s2, 0xffffe0
	v_lshrrev_b32_e32 v9, 2, v4
	v_lshlrev_b32_e32 v10, 1, v4
	v_and_b32_e32 v3, 1, v3
	v_and_or_b32 v5, v4, s2, v5
	v_and_b32_e32 v9, 4, v9
	v_and_b32_e32 v10, 24, v10
	v_add_u16_e32 v2, v2, v3
	v_or3_b32 v5, v5, v9, v10
	v_lshlrev_b32_e32 v9, 5, v6
	v_ashrrev_i16_sdwa v2, v212, sext(v2) dst_sel:DWORD dst_unused:UNUSED_PAD src0_sel:DWORD src1_sel:BYTE_0
	v_and_b32_e32 v9, 32, v9
	v_bfe_i32 v10, v2, 0, 16
	s_movk_i32 s3, 0x2b00
	v_mul_u32_u24_e32 v5, 0x2b00, v5
	v_add_u32_e32 v2, v9, v10
	v_mul_lo_u32 v3, v4, s3
	v_add_lshl_u32 v130, v5, v2, 1
	v_add_lshl_u32 v132, v2, v3, 1
	v_ashrrev_i32_e32 v2, 31, v0
	v_lshrrev_b32_e32 v2, 22, v2
	v_add_u32_e32 v2, v0, v2
	v_ashrrev_i32_e32 v11, 10, v2
	v_mul_i32_i24_e32 v2, 0x400, v11
	v_sub_u32_e32 v0, v0, v2
	v_lshrrev_b32_e32 v2, 4, v0
	v_bitop3_b32 v0, v2, v0, 32 bitop3:0x6c
	v_ashrrev_i32_e32 v2, 31, v0
	v_lshrrev_b32_e32 v2, 26, v2
	v_add_u32_e32 v2, v0, v2
	v_lshlrev_b32_e32 v3, 3, v11
	v_ashrrev_i32_e32 v12, 6, v2
	v_and_b32_e32 v3, -16, v3
	v_add_u32_e32 v3, v12, v3
	v_and_b32_e32 v4, 3, v12
	v_lshrrev_b32_e32 v5, 2, v3
	v_lshlrev_b32_e32 v13, 1, v3
	v_and_b32_e32 v2, 0xc0, v2
	v_and_or_b32 v4, v3, s2, v4
	v_and_b32_e32 v5, 4, v5
	v_and_b32_e32 v13, 24, v13
	v_sub_u32_e32 v0, v0, v2
	v_mul_lo_u32 v3, v3, s3
	v_readlane_b32 s3, v254, 12
	s_ashr_i32 s1, s0, 2
	v_or3_b32 v4, v4, v5, v13
	v_lshlrev_b32_e32 v5, 5, v11
	v_ashrrev_i16_sdwa v0, v212, sext(v0) dst_sel:DWORD dst_unused:UNUSED_PAD src0_sel:DWORD src1_sel:BYTE_0
	s_mul_i32 s2, s3, 0x560000
	v_and_b32_e32 v13, 32, v5
	v_bfe_i32 v14, v0, 0, 16
	s_add_u32 s16, s24, s2
	s_mul_hi_i32 s2, s3, 0x560000
	v_mul_u32_u24_e32 v4, 0x2b00, v4
	v_add_u32_e32 v2, v13, v14
	s_addc_u32 s17, s25, s2
	s_add_i32 s31, s26, 0
	v_add_lshl_u32 v0, v4, v2, 1
	s_add_i32 m0, s31, 0x10000
	v_add_lshl_u32 v134, v2, v3, 1
	global_load_lds_dwordx4 v0, s[16:17]
	s_add_i32 m0, s31, 0x12000
	s_add_u32 s2, s16, 0x2b0000
	global_load_lds_dwordx4 v130, s[16:17]
	s_addc_u32 s3, s17, 0
	s_add_i32 m0, s31, 0x14000
	s_add_i32 s36, s31, 0x2000
	global_load_lds_dwordx4 v0, s[2:3]
	s_add_i32 m0, s31, 0x16000
	s_add_i32 s37, s31, 0x4000
	global_load_lds_dwordx4 v130, s[2:3]
	v_readlane_b32 s2, v254, 32
	s_mov_b32 m0, s31
	v_readlane_b32 s3, v254, 33
	s_add_i32 s38, s31, 0x6000
	v_mov_b32_e32 v131, v1
	s_cmp_eq_u32 s1, 1
	v_lshl_add_u64 v[2:3], s[16:17], 0, v[0:1]
	v_lshl_add_u64 v[4:5], s[16:17], 0, v[130:131]
	global_load_lds_dwordx4 v134, s[2:3]
	s_mov_b32 m0, s36
	s_nop 0
	global_load_lds_dwordx4 v132, s[2:3]
	v_readlane_b32 s2, v254, 34
	s_mov_b32 m0, s37
	v_readlane_b32 s3, v254, 35
	s_nop 4
	global_load_lds_dwordx4 v134, s[2:3]
	s_mov_b32 m0, s38
	s_nop 0
	global_load_lds_dwordx4 v132, s[2:3]
	s_cselect_b64 s[2:3], -1, 0
	s_cmp_lg_u32 s1, 1
	s_cbranch_scc1 .LBB0_791
	s_barrier
	s_setprio 1

.LBB0_805:
	s_add_i32 s49, 0, 0x10000
	v_add_u32_e32 v140, s49, v143
	s_add_i32 s50, 0, 0x14000
	ds_read_b128 v[146:149], v140
	ds_read_b128 v[150:153], v140 offset:1024
	ds_read_b128 v[154:157], v140 offset:2048
	ds_read_b128 v[158:161], v140 offset:3072
	v_add_u32_e32 v140, s50, v143
	ds_read_b128 v[162:165], v140
	ds_read_b128 v[166:169], v140 offset:1024
	ds_read_b128 v[170:173], v140 offset:2048
	ds_read_b128 v[178:181], v140 offset:3072
	v_lshl_add_u64 v[140:141], s[14:15], 0, v[136:137]
	s_add_i32 m0, s31, 0xc000
	ds_read_b128 v[190:193], v145
	ds_read_b128 v[194:197], v145 offset:1024
	ds_read_b128 v[198:201], v145 offset:2048
	ds_read_b128 v[202:205], v145 offset:3072
	ds_read_b128 v[206:209], v145 offset:4096
	ds_read_b128 v[228:231], v145 offset:5120
	ds_read_b128 v[232:235], v145 offset:6144
	ds_read_b128 v[236:239], v145 offset:7168
	global_load_lds_dwordx4 v[140:141], off
	v_lshl_add_u64 v[140:141], s[14:15], 0, v[138:139]
	s_add_i32 m0, s31, 0xe000
	s_nop 0
	global_load_lds_dwordx4 v[140:141], off
	s_cmp_eq_u32 s48, -2
	s_cbranch_scc1 .Lz0_3_0
	s_waitcnt vmcnt(8)
	s_waitcnt lgkmcnt(0)
	s_barrier
	v_mfma_f32_16x16x32_bf16 v[126:129], v[146:149], v[190:193], v[126:129]
	v_mfma_f32_16x16x32_bf16 v[126:129], v[150:153], v[194:197], v[126:129]
	v_mfma_f32_16x16x32_bf16 v[118:121], v[150:153], v[202:205], v[118:121]
	v_mfma_f32_16x16x32_bf16 v[118:121], v[146:149], v[198:201], v[118:121]
	v_mfma_f32_16x16x32_bf16 v[102:105], v[146:149], v[206:209], v[102:105]
	v_mfma_f32_16x16x32_bf16 v[102:105], v[150:153], v[228:231], v[102:105]
	v_mfma_f32_16x16x32_bf16 v[86:89], v[150:153], v[236:239], v[86:89]
	v_mfma_f32_16x16x32_bf16 v[86:89], v[146:149], v[232:235], v[86:89]
	v_mfma_f32_16x16x32_bf16 v[78:81], v[154:157], v[232:235], v[78:81]
	v_mfma_f32_16x16x32_bf16 v[78:81], v[158:161], v[236:239], v[78:81]
	v_mfma_f32_16x16x32_bf16 v[94:97], v[158:161], v[228:231], v[94:97]
	v_mfma_f32_16x16x32_bf16 v[94:97], v[154:157], v[206:209], v[94:97]
	v_mfma_f32_16x16x32_bf16 v[110:113], v[154:157], v[198:201], v[110:113]
	v_mfma_f32_16x16x32_bf16 v[110:113], v[158:161], v[202:205], v[110:113]
	v_mfma_f32_16x16x32_bf16 v[122:125], v[158:161], v[194:197], v[122:125]
	v_mfma_f32_16x16x32_bf16 v[122:125], v[154:157], v[190:193], v[122:125]
	v_mfma_f32_16x16x32_bf16 v[114:117], v[162:165], v[190:193], v[114:117]
	v_mfma_f32_16x16x32_bf16 v[114:117], v[166:169], v[194:197], v[114:117]
	v_mfma_f32_16x16x32_bf16 v[98:101], v[166:169], v[202:205], v[98:101]
	v_mfma_f32_16x16x32_bf16 v[98:101], v[162:165], v[198:201], v[98:101]
	v_mfma_f32_16x16x32_bf16 v[82:85], v[162:165], v[206:209], v[82:85]
	v_mfma_f32_16x16x32_bf16 v[82:85], v[166:169], v[228:231], v[82:85]
	v_mfma_f32_16x16x32_bf16 v[70:73], v[166:169], v[236:239], v[70:73]
	v_mfma_f32_16x16x32_bf16 v[70:73], v[162:165], v[232:235], v[70:73]
	v_mfma_f32_16x16x32_bf16 v[66:69], v[170:173], v[232:235], v[66:69]
	v_mfma_f32_16x16x32_bf16 v[66:69], v[178:181], v[236:239], v[66:69]
	v_mfma_f32_16x16x32_bf16 v[74:77], v[178:181], v[228:231], v[74:77]
	v_mfma_f32_16x16x32_bf16 v[74:77], v[170:173], v[206:209], v[74:77]
	v_mfma_f32_16x16x32_bf16 v[90:93], v[170:173], v[198:201], v[90:93]
	v_mfma_f32_16x16x32_bf16 v[90:93], v[178:181], v[202:205], v[90:93]
	v_mfma_f32_16x16x32_bf16 v[106:109], v[178:181], v[194:197], v[106:109]
	v_mfma_f32_16x16x32_bf16 v[106:109], v[170:173], v[190:193], v[106:109]
	s_barrier
.Lz0_3_0_ret:
	s_add_i32 s14, s49, s26
	v_lshl_add_u64 v[140:141], s[18:19], 0, v[0:1]
	s_mov_b32 m0, s14
	s_nop 0
	global_load_lds_dwordx4 v[140:141], off
	ds_read_b128 v[190:193], v145 offset:16384
	ds_read_b128 v[194:197], v145 offset:17408
	s_add_i32 m0, s14, 0x2000
	s_add_u32 s14, s18, 0x2b0000
	v_lshl_add_u64 v[186:187], s[18:19], 0, v[130:131]
	s_addc_u32 s15, s19, 0
	s_add_i32 s49, s50, s26
	global_load_lds_dwordx4 v[186:187], off
	ds_read_b128 v[198:201], v145 offset:18432
	ds_read_b128 v[202:205], v145 offset:19456
	v_lshl_add_u64 v[188:189], s[14:15], 0, v[0:1]
	s_mov_b32 m0, s49
	v_lshl_add_u64 v[210:211], s[22:23], 0, v[132:133]
	global_load_lds_dwordx4 v[188:189], off
	ds_read_b128 v[206:209], v145 offset:20480
	ds_read_b128 v[228:231], v145 offset:21504
	v_lshl_add_u64 v[188:189], s[14:15], 0, v[130:131]
	s_add_i32 m0, s49, 0x2000
	s_nop 0
	global_load_lds_dwordx4 v[188:189], off
	ds_read_b128 v[232:235], v145 offset:22528
	ds_read_b128 v[236:239], v145 offset:23552
	v_lshl_add_u64 v[188:189], s[22:23], 0, v[134:135]
	s_mov_b32 m0, s31
	s_nop 0
	global_load_lds_dwordx4 v[188:189], off
	s_mov_b32 m0, s36
	s_nop 0
	global_load_lds_dwordx4 v[210:211], off
	s_cmp_eq_u32 s48, -2
	s_cbranch_scc1 .Lz0_3_1
	s_waitcnt vmcnt(8)
	s_waitcnt lgkmcnt(0)
	s_barrier
	v_mfma_f32_16x16x32_bf16 v[62:65], v[146:149], v[190:193], v[62:65]
	v_mfma_f32_16x16x32_bf16 v[62:65], v[150:153], v[194:197], v[62:65]
	v_mfma_f32_16x16x32_bf16 v[54:57], v[150:153], v[202:205], v[54:57]
	v_mfma_f32_16x16x32_bf16 v[54:57], v[146:149], v[198:201], v[54:57]
	v_mfma_f32_16x16x32_bf16 v[38:41], v[146:149], v[206:209], v[38:41]
	v_mfma_f32_16x16x32_bf16 v[38:41], v[150:153], v[228:231], v[38:41]
	v_mfma_f32_16x16x32_bf16 v[22:25], v[150:153], v[236:239], v[22:25]
	v_mfma_f32_16x16x32_bf16 v[22:25], v[146:149], v[232:235], v[22:25]
	v_mfma_f32_16x16x32_bf16 v[14:17], v[154:157], v[232:235], v[14:17]
	v_mfma_f32_16x16x32_bf16 v[14:17], v[158:161], v[236:239], v[14:17]
	v_mfma_f32_16x16x32_bf16 v[30:33], v[158:161], v[228:231], v[30:33]
	v_mfma_f32_16x16x32_bf16 v[30:33], v[154:157], v[206:209], v[30:33]
	v_mfma_f32_16x16x32_bf16 v[46:49], v[154:157], v[198:201], v[46:49]
	v_mfma_f32_16x16x32_bf16 v[46:49], v[158:161], v[202:205], v[46:49]
	v_mfma_f32_16x16x32_bf16 v[58:61], v[158:161], v[194:197], v[58:61]
	v_mfma_f32_16x16x32_bf16 v[58:61], v[154:157], v[190:193], v[58:61]
	v_mfma_f32_16x16x32_bf16 v[50:53], v[162:165], v[190:193], v[50:53]
	v_mfma_f32_16x16x32_bf16 v[50:53], v[166:169], v[194:197], v[50:53]
	v_mfma_f32_16x16x32_bf16 v[34:37], v[166:169], v[202:205], v[34:37]
	v_mfma_f32_16x16x32_bf16 v[34:37], v[162:165], v[198:201], v[34:37]
	v_mfma_f32_16x16x32_bf16 v[18:21], v[162:165], v[206:209], v[18:21]
	v_mfma_f32_16x16x32_bf16 v[18:21], v[166:169], v[228:231], v[18:21]
	v_mfma_f32_16x16x32_bf16 v[6:9], v[166:169], v[236:239], v[6:9]
	v_mfma_f32_16x16x32_bf16 v[6:9], v[162:165], v[232:235], v[6:9]
	v_mfma_f32_16x16x32_bf16 v[2:5], v[170:173], v[232:235], v[2:5]
	v_mfma_f32_16x16x32_bf16 v[2:5], v[178:181], v[236:239], v[2:5]
	v_mfma_f32_16x16x32_bf16 v[10:13], v[178:181], v[228:231], v[10:13]
	v_mfma_f32_16x16x32_bf16 v[10:13], v[170:173], v[206:209], v[10:13]
	v_mfma_f32_16x16x32_bf16 v[26:29], v[170:173], v[198:201], v[26:29]
	v_mfma_f32_16x16x32_bf16 v[26:29], v[178:181], v[202:205], v[26:29]
	v_mfma_f32_16x16x32_bf16 v[42:45], v[178:181], v[194:197], v[42:45]
	v_mfma_f32_16x16x32_bf16 v[42:45], v[170:173], v[190:193], v[42:45]
	s_barrier
.Lz0_3_1_ret:
	s_add_i32 s49, 0, 0x18000
	s_add_i32 s50, 0, 0x1c000
	v_add_u32_e32 v158, s49, v143
	v_add_u32_e32 v175, s50, v143
	ds_read_b128 v[146:149], v158
	ds_read_b128 v[150:153], v158 offset:1024
	ds_read_b128 v[154:157], v158 offset:2048
	ds_read_b128 v[158:161], v158 offset:3072
	ds_read_b128 v[162:165], v175
	ds_read_b128 v[166:169], v175 offset:1024
	ds_read_b128 v[170:173], v175 offset:2048
	ds_read_b128 v[178:181], v175 offset:3072
	s_add_u32 s14, s22, 0x2b0000
	s_addc_u32 s15, s23, 0
	s_mov_b32 m0, s37
	v_lshl_add_u64 v[226:227], s[14:15], 0, v[134:135]
	ds_read_b128 v[190:193], v145 offset:32768
	ds_read_b128 v[194:197], v145 offset:33792
	ds_read_b128 v[198:201], v145 offset:34816
	ds_read_b128 v[202:205], v145 offset:35840
	ds_read_b128 v[206:209], v145 offset:36864
	ds_read_b128 v[228:231], v145 offset:37888
	ds_read_b128 v[232:235], v145 offset:38912
	ds_read_b128 v[236:239], v145 offset:39936
	global_load_lds_dwordx4 v[226:227], off
	v_lshl_add_u64 v[226:227], s[14:15], 0, v[132:133]
	s_mov_b32 m0, s38
	s_nop 0
	global_load_lds_dwordx4 v[226:227], off
	s_waitcnt vmcnt(8)
	s_waitcnt lgkmcnt(0)
	s_barrier
	v_mfma_f32_16x16x32_bf16 v[126:129], v[146:149], v[190:193], v[126:129]
	v_mfma_f32_16x16x32_bf16 v[126:129], v[150:153], v[194:197], v[126:129]
	v_mfma_f32_16x16x32_bf16 v[118:121], v[150:153], v[202:205], v[118:121]
	v_mfma_f32_16x16x32_bf16 v[118:121], v[146:149], v[198:201], v[118:121]
	v_mfma_f32_16x16x32_bf16 v[102:105], v[146:149], v[206:209], v[102:105]
	v_mfma_f32_16x16x32_bf16 v[102:105], v[150:153], v[228:231], v[102:105]
	v_mfma_f32_16x16x32_bf16 v[86:89], v[150:153], v[236:239], v[86:89]
	v_mfma_f32_16x16x32_bf16 v[86:89], v[146:149], v[232:235], v[86:89]
	v_mfma_f32_16x16x32_bf16 v[78:81], v[154:157], v[232:235], v[78:81]
	v_mfma_f32_16x16x32_bf16 v[78:81], v[158:161], v[236:239], v[78:81]
	v_mfma_f32_16x16x32_bf16 v[94:97], v[158:161], v[228:231], v[94:97]
	v_mfma_f32_16x16x32_bf16 v[94:97], v[154:157], v[206:209], v[94:97]
	v_mfma_f32_16x16x32_bf16 v[110:113], v[154:157], v[198:201], v[110:113]
	v_mfma_f32_16x16x32_bf16 v[110:113], v[158:161], v[202:205], v[110:113]
	v_mfma_f32_16x16x32_bf16 v[122:125], v[158:161], v[194:197], v[122:125]
	v_mfma_f32_16x16x32_bf16 v[122:125], v[154:157], v[190:193], v[122:125]
	v_mfma_f32_16x16x32_bf16 v[114:117], v[162:165], v[190:193], v[114:117]
	v_mfma_f32_16x16x32_bf16 v[114:117], v[166:169], v[194:197], v[114:117]
	v_mfma_f32_16x16x32_bf16 v[98:101], v[166:169], v[202:205], v[98:101]
	v_mfma_f32_16x16x32_bf16 v[98:101], v[162:165], v[198:201], v[98:101]
	v_mfma_f32_16x16x32_bf16 v[82:85], v[162:165], v[206:209], v[82:85]
	v_mfma_f32_16x16x32_bf16 v[82:85], v[166:169], v[228:231], v[82:85]
	v_mfma_f32_16x16x32_bf16 v[70:73], v[166:169], v[236:239], v[70:73]
	v_mfma_f32_16x16x32_bf16 v[70:73], v[162:165], v[232:235], v[70:73]
	v_mfma_f32_16x16x32_bf16 v[66:69], v[170:173], v[232:235], v[66:69]
	v_mfma_f32_16x16x32_bf16 v[66:69], v[178:181], v[236:239], v[66:69]
	v_mfma_f32_16x16x32_bf16 v[74:77], v[178:181], v[228:231], v[74:77]
	v_mfma_f32_16x16x32_bf16 v[74:77], v[170:173], v[206:209], v[74:77]
	v_mfma_f32_16x16x32_bf16 v[90:93], v[170:173], v[198:201], v[90:93]
	v_mfma_f32_16x16x32_bf16 v[90:93], v[178:181], v[202:205], v[90:93]
	v_mfma_f32_16x16x32_bf16 v[106:109], v[178:181], v[194:197], v[106:109]
	v_mfma_f32_16x16x32_bf16 v[106:109], v[170:173], v[190:193], v[106:109]
	s_barrier
	s_add_i32 s14, s49, s26
	v_lshl_add_u64 v[140:141], v[140:141], 0, s[34:35]
	s_mov_b32 m0, s14
	s_nop 0
	global_load_lds_dwordx4 v[140:141], off
	ds_read_b128 v[190:193], v145 offset:49152
	ds_read_b128 v[194:197], v145 offset:50176
	s_add_i32 m0, s14, 0x2000
	s_add_u32 s14, s18, 0x2b0080
	v_lshl_add_u64 v[140:141], v[186:187], 0, s[34:35]
	s_addc_u32 s15, s19, 0
	s_add_i32 s18, s50, s26
	global_load_lds_dwordx4 v[140:141], off
	ds_read_b128 v[198:201], v145 offset:51200
	ds_read_b128 v[202:205], v145 offset:52224
	v_lshl_add_u64 v[140:141], s[14:15], 0, v[0:1]
	s_mov_b32 m0, s18
	s_nop 0
	global_load_lds_dwordx4 v[140:141], off
	ds_read_b128 v[206:209], v145 offset:53248
	ds_read_b128 v[228:231], v145 offset:54272
	v_lshl_add_u64 v[140:141], s[14:15], 0, v[130:131]
	s_add_i32 m0, s18, 0x2000
	s_nop 0
	global_load_lds_dwordx4 v[140:141], off
	ds_read_b128 v[232:235], v145 offset:55296
	ds_read_b128 v[236:239], v145 offset:56320
	v_lshl_add_u64 v[140:141], v[188:189], 0, s[34:35]
	s_mov_b32 m0, s39
	s_nop 0
	global_load_lds_dwordx4 v[140:141], off
	s_add_i32 s48, s48, 2
	s_add_u32 s46, s46, 0x100
	s_addc_u32 s47, s47, 0
	s_mov_b64 s[14:15], s[16:17]
	s_add_u32 s16, s14, 0x100
	s_addc_u32 s17, s15, 0
	s_cmpk_eq_i32 s48, 0xa8
	s_cselect_b32 s23, s5, s17
	s_cselect_b32 s22, s4, s16
	s_cselect_b32 s19, s9, s47
	s_cselect_b32 s18, s8, s46
	v_lshl_add_u64 v[140:141], v[210:211], 0, s[34:35]
	s_mov_b32 m0, s40
	s_nop 0
	global_load_lds_dwordx4 v[140:141], off
	s_waitcnt vmcnt(8)
	s_waitcnt lgkmcnt(0)
	s_barrier
	v_mfma_f32_16x16x32_bf16 v[62:65], v[146:149], v[190:193], v[62:65]
	v_mfma_f32_16x16x32_bf16 v[62:65], v[150:153], v[194:197], v[62:65]
	v_mfma_f32_16x16x32_bf16 v[54:57], v[150:153], v[202:205], v[54:57]
	v_mfma_f32_16x16x32_bf16 v[54:57], v[146:149], v[198:201], v[54:57]
	v_mfma_f32_16x16x32_bf16 v[38:41], v[146:149], v[206:209], v[38:41]
	v_mfma_f32_16x16x32_bf16 v[38:41], v[150:153], v[228:231], v[38:41]
	v_mfma_f32_16x16x32_bf16 v[22:25], v[150:153], v[236:239], v[22:25]
	v_mfma_f32_16x16x32_bf16 v[22:25], v[146:149], v[232:235], v[22:25]
	v_mfma_f32_16x16x32_bf16 v[14:17], v[154:157], v[232:235], v[14:17]
	v_mfma_f32_16x16x32_bf16 v[14:17], v[158:161], v[236:239], v[14:17]
	v_mfma_f32_16x16x32_bf16 v[30:33], v[158:161], v[228:231], v[30:33]
	v_mfma_f32_16x16x32_bf16 v[30:33], v[154:157], v[206:209], v[30:33]
	v_mfma_f32_16x16x32_bf16 v[46:49], v[154:157], v[198:201], v[46:49]
	v_mfma_f32_16x16x32_bf16 v[46:49], v[158:161], v[202:205], v[46:49]
	v_mfma_f32_16x16x32_bf16 v[58:61], v[158:161], v[194:197], v[58:61]
	v_mfma_f32_16x16x32_bf16 v[58:61], v[154:157], v[190:193], v[58:61]
	v_mfma_f32_16x16x32_bf16 v[50:53], v[162:165], v[190:193], v[50:53]
	v_mfma_f32_16x16x32_bf16 v[50:53], v[166:169], v[194:197], v[50:53]
	v_mfma_f32_16x16x32_bf16 v[34:37], v[166:169], v[202:205], v[34:37]
	v_mfma_f32_16x16x32_bf16 v[34:37], v[162:165], v[198:201], v[34:37]
	v_mfma_f32_16x16x32_bf16 v[18:21], v[162:165], v[206:209], v[18:21]
	v_mfma_f32_16x16x32_bf16 v[18:21], v[166:169], v[228:231], v[18:21]
	v_mfma_f32_16x16x32_bf16 v[6:9], v[166:169], v[236:239], v[6:9]
	v_mfma_f32_16x16x32_bf16 v[6:9], v[162:165], v[232:235], v[6:9]
	v_mfma_f32_16x16x32_bf16 v[2:5], v[170:173], v[232:235], v[2:5]
	v_mfma_f32_16x16x32_bf16 v[2:5], v[178:181], v[236:239], v[2:5]
	v_mfma_f32_16x16x32_bf16 v[10:13], v[178:181], v[228:231], v[10:13]
	v_mfma_f32_16x16x32_bf16 v[10:13], v[170:173], v[206:209], v[10:13]
	v_mfma_f32_16x16x32_bf16 v[26:29], v[170:173], v[198:201], v[26:29]
	v_mfma_f32_16x16x32_bf16 v[26:29], v[178:181], v[202:205], v[26:29]
	v_mfma_f32_16x16x32_bf16 v[42:45], v[178:181], v[194:197], v[42:45]
	v_mfma_f32_16x16x32_bf16 v[42:45], v[170:173], v[190:193], v[42:45]
	s_barrier
	s_cmpk_gt_u32 s48, 0xa9
	s_cbranch_scc0 .LBB0_805
	s_and_b64 vcc, exec, s[6:7]
	s_cbranch_vccz .LBB0_808
	s_barrier
